# LRU pass 0: gate scale/bias folded into the gate MFMAs (conv tile written as bf16(-log2e*xc), bias row as initial C), constants read once per sweep, next step's MFMAs issued under the previous scan; o
# baseline (speedup 1.0000x reference)
; #define LAS __attribute__((address_space(3)))
; template <int PASS> __device__ __forceinline__ void phase_lru(LAS unsigned char* lds, const bf16_t* Z, const bf16_t* WL, float* LSUM, const float* LCAR, bf16_t* RNN,
;                                                               int S, int tid, int lane, int wave, int G) {
;     ...
;         const int ch0 = n * 128 + wave * 16 + 4 * g4;
;         bf16x8 wf[4][4];
; #pragma unroll
;         for (int q = 0; q < 4; ++q)
; #pragma unroll
;             for (int s = 0; s < 4; ++s) wf[q][s] = *(const bf16x8*)(WL + ((size_t)((n * 4 + q) * 128 + wave * 16 + c)) * 128 + 32 * s + 8 * g4);
;         LAS f32x4* kc = (LAS f32x4*)(lds + LRU_KC + wave * 11264);
; #pragma unroll
;         for (int k = 0; k < 4; ++k) kc[(6 + k) * 64 + lane] = *(const f32x4*)(conv_w + k * LW + ch0);
;         kc[10 * 64 + lane] = *(const f32x4*)(conv_b + ch0);
; #pragma unroll
;         for (int d = 0; d < 2; ++d) { kc[(3 * d + 0) * 64 + lane] = *(const f32x4*)(lba + d * LW + ch0) * (-LOG2E); kc[(3 * d + 1) * 64 + lane] = *(const f32x4*)(lbx + d * LW + ch0) * (-LOG2E);
;             const f32x4 lv = *(const f32x4*)(lam + d * LW + ch0); f32x4 sp;
; #pragma unroll
;             for (int j = 0; j < 4; ++j) sp[j] = -8.0f * LOG2E * log1pf(expf(-lv[j]));
;             kc[(3 * d + 2) * 64 + lane] = sp; }
;     ...
;         u32x4 rawr[3];
;     ...
;         LRU_LOAD_RAW(run * 4)
.LBB0_213:
	s_ashr_i32 s0, s57, 6
	v_lshl_add_u32 v2, s0, 9, v154
	v_ashrrev_i32_e32 v3, 31, v2
	v_lshlrev_b64 v[4:5], 8, v[2:3]
	v_add_u32_e32 v20, 0x80, v2
	v_add_u32_e32 v36, 0x100, v2
	v_add_u32_e32 v2, 0x180, v2
	s_lshl_b32 s58, s0, 7
	v_ashrrev_i32_e32 v21, 31, v20
	v_ashrrev_i32_e32 v37, 31, v36
	v_ashrrev_i32_e32 v3, 31, v2
	v_lshlrev_b64 v[20:21], 8, v[20:21]
	v_lshlrev_b64 v[36:37], 8, v[36:37]
	v_lshlrev_b64 v[2:3], 8, v[2:3]
	v_add_u32_e32 v80, s58, v153
	v_lshl_add_u64 v[16:17], v[100:101], 0, v[4:5]
	v_lshl_add_u64 v[32:33], v[100:101], 0, v[20:21]
	v_lshl_add_u64 v[48:49], v[100:101], 0, v[36:37]
	v_lshl_add_u64 v[2:3], v[100:101], 0, v[2:3]
	v_ashrrev_i32_e32 v81, 31, v80
	global_load_dwordx4 v[4:7], v[16:17], off
	global_load_dwordx4 v[8:11], v[16:17], off offset:64
	global_load_dwordx4 v[12:15], v[16:17], off offset:128
	s_nop 0
	global_load_dwordx4 v[16:19], v[16:17], off offset:192
	s_nop 0
	global_load_dwordx4 v[20:23], v[32:33], off
	global_load_dwordx4 v[24:27], v[32:33], off offset:64
	global_load_dwordx4 v[28:31], v[32:33], off offset:128
	s_nop 0
	global_load_dwordx4 v[32:35], v[32:33], off offset:192
	s_nop 0
	global_load_dwordx4 v[36:39], v[48:49], off
	global_load_dwordx4 v[40:43], v[48:49], off offset:64
	global_load_dwordx4 v[44:47], v[48:49], off offset:128
	s_nop 0
	global_load_dwordx4 v[48:51], v[48:49], off offset:192
	s_nop 0
	global_load_dwordx4 v[52:55], v[2:3], off
	global_load_dwordx4 v[56:59], v[2:3], off offset:64
	global_load_dwordx4 v[60:63], v[2:3], off offset:128
	global_load_dwordx4 v[64:67], v[2:3], off offset:192
	s_ashr_i32 s59, s58, 31
	v_lshlrev_b32_e32 v82, 1, v102
	s_lshl_b32 s0, s57, 8
	s_and_b32 s18, s0, 0x3f00
	s_and_b32 s19, s18, s30
	s_add_i32 s19, s19, -2
	v_add_u32_e32 v1, s19, v156
	v_mov_b32_e32 v2, v0
	v_mov_b32_e32 v3, v0
	v_cmp_gt_u32_e32 vcc, s62, v1
	v_mov_b32_e32 v1, v0
	v_mov_b64_e32 v[70:71], v[2:3]
	s_add_i32 s18, s18, -2
	s_and_b64 s[78:79], s[42:43], vcc
	v_mov_b64_e32 v[68:69], v[0:1]
	s_and_saveexec_b64 s[0:1], s[78:79]
	s_cbranch_execz .LBB0_215
	v_add_u32_e32 v70, s18, v156
	v_mov_b64_e32 v[68:69], s[92:93]
	v_mad_i64_i32 v[68:69], s[78:79], v70, s27, v[68:69]
	v_lshl_add_u64 v[68:69], s[58:59], 1, v[68:69]
	v_mov_b32_e32 v83, v0
	v_lshl_add_u64 v[68:69], v[68:69], 0, v[82:83]
	v_add_co_u32_e32 v68, vcc, 0x2000, v68
	s_nop 1
	v_addc_co_u32_e32 v69, vcc, 0, v69, vcc
	global_load_dwordx4 v[68:71], v[68:69], off offset:1024

; #define LAS __attribute__((address_space(3)))
; template <int PASS> __device__ __forceinline__ void phase_lru(LAS unsigned char* lds, const bf16_t* Z, const bf16_t* WL, float* LSUM, const float* LCAR, bf16_t* RNN,
;                                                               int S, int tid, int lane, int wave, int G) {
;     ...
;         LAS f32x4* kc = (LAS f32x4*)(lds + LRU_KC + wave * 11264);
; #pragma unroll
;         for (int k = 0; k < 4; ++k) kc[(6 + k) * 64 + lane] = *(const f32x4*)(conv_w + k * LW + ch0);
;         kc[10 * 64 + lane] = *(const f32x4*)(conv_b + ch0);
; #pragma unroll
;         for (int d = 0; d < 2; ++d) { kc[(3 * d + 0) * 64 + lane] = *(const f32x4*)(lba + d * LW + ch0) * (-LOG2E); kc[(3 * d + 1) * 64 + lane] = *(const f32x4*)(lbx + d * LW + ch0) * (-LOG2E);
;             const f32x4 lv = *(const f32x4*)(lam + d * LW + ch0); f32x4 sp;
; #pragma unroll
;             for (int j = 0; j < 4; ++j) sp[j] = -8.0f * LOG2E * log1pf(expf(-lv[j]));
;             kc[(3 * d + 2) * 64 + lane] = sp; }
.LBB0_219:
	s_or_b64 exec, exec, s[0:1]
	v_lshlrev_b64 v[2:3], 2, v[80:81]
	v_add_u32_e32 v1, 0x1800, v2
	v_add_u32_e32 v3, 0x3000, v2
	v_add_u32_e32 v106, 0x4800, v2
	global_load_dwordx4 v[216:219], v2, s[4:5]
	global_load_dwordx4 v[220:223], v1, s[4:5]
	global_load_dwordx4 v[224:227], v3, s[4:5]
	global_load_dwordx4 v[84:87], v106, s[4:5]
	global_load_dwordx4 v[88:91], v2, s[12:13]
	global_load_dwordx4 v[92:95], v2, s[36:37]
	global_load_dwordx4 v[96:99], v2, s[94:95]
	global_load_dwordx4 v[108:111], v2, s[96:97]
	global_load_dwordx4 v[204:207], v1, s[36:37]
	global_load_dwordx4 v[208:211], v1, s[94:95]
	global_load_dwordx4 v[212:215], v1, s[96:97]
	s_mov_b32 s76, 0xc1000000
	s_waitcnt vmcnt(0)
	ds_write_b128 v155, v[216:219] offset:43008
	ds_write_b128 v155, v[220:223] offset:44032
	ds_write_b128 v155, v[224:227] offset:45056
	ds_write_b128 v155, v[84:87] offset:46080
	ds_write_b128 v155, v[88:91] offset:47104
	v_pk_mul_f32 v[92:93], v[92:93], s[24:25] op_sel_hi:[1,0]
	v_pk_mul_f32 v[94:95], v[94:95], s[24:25] op_sel_hi:[1,0]
	v_pk_mul_f32 v[96:97], v[96:97], s[24:25] op_sel_hi:[1,0]
	v_pk_mul_f32 v[98:99], v[98:99], s[24:25] op_sel_hi:[1,0]
	v_pk_mul_f32 v[204:205], v[204:205], s[24:25] op_sel_hi:[1,0]
	v_pk_mul_f32 v[206:207], v[206:207], s[24:25] op_sel_hi:[1,0]
	v_pk_mul_f32 v[208:209], v[208:209], s[24:25] op_sel_hi:[1,0]
	v_pk_mul_f32 v[210:211], v[210:211], s[24:25] op_sel_hi:[1,0]
	ds_write_b128 v155, v[92:95] offset:36864
	ds_write_b128 v155, v[96:99] offset:37888
	ds_write_b128 v155, v[204:207] offset:39936
	ds_write_b128 v155, v[208:211] offset:40960
	v_mul_f32_e32 v216, s24, v108
	v_mul_f32_e32 v217, s24, v109
	v_mul_f32_e32 v218, s24, v110
	v_mul_f32_e32 v219, s24, v111
	v_mul_f32_e32 v220, s24, v212
	v_mul_f32_e32 v221, s24, v213
	v_mul_f32_e32 v222, s24, v214
	v_mul_f32_e32 v223, s24, v215
	v_exp_f32_e32 v216, v216
	v_exp_f32_e32 v217, v217
	v_exp_f32_e32 v218, v218
	v_exp_f32_e32 v219, v219
	v_exp_f32_e32 v220, v220
	v_exp_f32_e32 v221, v221
	v_exp_f32_e32 v222, v222
	v_exp_f32_e32 v223, v223
	v_add_f32_e32 v224, 1.0, v216
	v_add_f32_e32 v225, 1.0, v217
	v_add_f32_e32 v226, 1.0, v218
	v_add_f32_e32 v227, 1.0, v219
	v_add_f32_e32 v84, 1.0, v220
	v_add_f32_e32 v85, 1.0, v221
	v_add_f32_e32 v86, 1.0, v222
	v_add_f32_e32 v87, 1.0, v223
	v_add_f32_e32 v88, -1.0, v224
	v_add_f32_e32 v89, -1.0, v225
	v_add_f32_e32 v90, -1.0, v226
	v_add_f32_e32 v91, -1.0, v227
	v_add_f32_e32 v92, -1.0, v84
	v_add_f32_e32 v93, -1.0, v85
	v_add_f32_e32 v94, -1.0, v86
	v_add_f32_e32 v95, -1.0, v87
	v_log_f32_e32 v224, v224
	v_log_f32_e32 v225, v225
	v_log_f32_e32 v226, v226
	v_log_f32_e32 v227, v227
	v_log_f32_e32 v84, v84
	v_log_f32_e32 v85, v85
	v_log_f32_e32 v86, v86
	v_log_f32_e32 v87, v87
	v_max_f32_e32 v88, 0x33800000, v88
	v_max_f32_e32 v89, 0x33800000, v89
	v_max_f32_e32 v90, 0x33800000, v90
	v_max_f32_e32 v91, 0x33800000, v91
	v_max_f32_e32 v92, 0x33800000, v92
	v_max_f32_e32 v93, 0x33800000, v93
	v_max_f32_e32 v94, 0x33800000, v94
	v_max_f32_e32 v95, 0x33800000, v95
	v_rcp_f32_e32 v88, v88
	v_rcp_f32_e32 v89, v89
	v_rcp_f32_e32 v90, v90
	v_rcp_f32_e32 v91, v91
	v_rcp_f32_e32 v92, v92
	v_rcp_f32_e32 v93, v93
	v_rcp_f32_e32 v94, v94
	v_rcp_f32_e32 v95, v95
	v_mul_f32_e32 v216, v216, v88
	v_mul_f32_e32 v217, v217, v89
	v_mul_f32_e32 v218, v218, v90
	v_mul_f32_e32 v219, v219, v91
	v_mul_f32_e32 v220, v220, v92
	v_mul_f32_e32 v221, v221, v93
	v_mul_f32_e32 v222, v222, v94
	v_mul_f32_e32 v223, v223, v95
	v_mul_f32_e32 v224, v224, v216
	v_mul_f32_e32 v225, v225, v217
	v_mul_f32_e32 v226, v226, v218
	v_mul_f32_e32 v227, v227, v219
	v_mul_f32_e32 v84, v84, v220
	v_mul_f32_e32 v85, v85, v221
	v_mul_f32_e32 v86, v86, v222
	v_mul_f32_e32 v87, v87, v223
	v_mul_f32_e32 v108, s76, v224
	v_mul_f32_e32 v109, s76, v225
	v_mul_f32_e32 v110, s76, v226
	v_mul_f32_e32 v111, s76, v227
	v_mul_f32_e32 v212, s76, v84
	v_mul_f32_e32 v213, s76, v85
	v_mul_f32_e32 v214, s76, v86
	v_mul_f32_e32 v215, s76, v87
	ds_write_b128 v155, v[108:111] offset:38912
	ds_write_b128 v155, v[212:215] offset:41984
	s_bfe_u32 s0, s54, 0x60002
	s_lshl_b32 s1, s0, 8
	v_add_u32_e32 v1, s1, v159
	v_lshlrev_b64 v[2:3], 3, v[80:81]
	v_add_u32_e32 v82, s1, v160
	v_add_u32_e32 v83, s1, v161
	s_or_b32 s28, s1, 64
	v_mad_u64_u32 v[2:3], s[0:1], s0, v198, v[2:3]
	v_mad_i64_i32 v[80:81], s[0:1], v1, s27, v[104:105]
	s_lshl_b64 s[0:1], s[58:59], 1
	s_nop 0
	v_lshl_add_u64 v[108:109], v[80:81], 0, s[0:1]
	v_mad_i64_i32 v[80:81], s[18:19], v82, s27, v[104:105]
	v_lshl_add_u64 v[110:111], v[80:81], 0, s[0:1]
	v_mad_i64_i32 v[80:81], s[18:19], v83, s27, v[104:105]
	v_lshl_add_u64 v[106:107], s[88:89], 0, v[2:3]
	v_lshl_add_u64 v[112:113], v[80:81], 0, s[0:1]
	s_mov_b64 s[0:1], 0
	s_branch .LBB0_221

; #define LAS __attribute__((address_space(3)))
; __device__ __forceinline__ unsigned pk2(float lo, float hi) { return pg8::cvt_pk_bf16(lo, hi); }
; __device__ __forceinline__ float bflo(unsigned w) { return __uint_as_float(w << 16); }
; __device__ __forceinline__ float bfhi(unsigned w) { return __uint_as_float(w & 0xffff0000u); }
; #define LRU_BAR() do { asm volatile("s_waitcnt lgkmcnt(0)" ::: "memory"); __builtin_amdgcn_s_barrier(); asm volatile("" ::: "memory"); } while (0)
; template <int PASS> __device__ __forceinline__ void phase_lru(LAS unsigned char* lds, const bf16_t* Z, const bf16_t* WL, float* LSUM, const float* LCAR, bf16_t* RNN,
;                                                               int S, int tid, int lane, int wave, int G) {
;     ...
; #pragma unroll
;             for (int i = 0; i < 3; ++i) { const int idx = tid + 512 * i; if (idx < 67 * 16) *(LAS u32x4*)(lds + LRU_RAW + (idx >> 4) * LRU_RAWP + 16 * (idx & 15)) = rawr[i]; }
;             u32x2 ryr[4]; f32x4 car[2];
;             if (PASS == 1) {
; #pragma unroll
;                 for (int t = 0; t < 4; ++t) ryr[t] = *(const u32x2*)(Z + (size_t)(t0 + 16 * t + c) * DIN + C_RY + ch0);
;                 car[0] = *(const f32x4*)(LCAR + (size_t)(seg * 2 + 0) * LW + ch0); car[1] = *(const f32x4*)(LCAR + (size_t)(seg * 2 + 1) * LW + ch0);
;             }
;             LRU_BAR();
;             f32x4 cw[4], cb;
; #pragma unroll
;             for (int k = 0; k < 4; ++k) cw[k] = kc[(6 + k) * 64 + lane];
;             cb = kc[10 * 64 + lane];
;             f32x4 xc[4];
; #pragma unroll
;             for (int t = 0; t < 4; ++t) { f32x4 acc = cb;
; #pragma unroll
;                 for (int k = 0; k < 4; ++k) { const u32x2 rw = *(const LAS u32x2*)(lds + LRU_RAW + (16 * t + c + k) * LRU_RAWP + (wave * 16 + 4 * g4) * 2);
;                     acc = acc + (f32x4){bflo(rw.x), bfhi(rw.x), bflo(rw.y), bfhi(rw.y)} * cw[k]; }
;                 xc[t] = acc;
;                 u32x2 w; w.x = pk2(acc[0], acc[1]); w.y = pk2(acc[2], acc[3]);
;                 *(LAS u32x2*)(lds + LRU_XC + off_b(16 * t + c, 2 * wave + (g4 >> 1)) + 8 * (g4 & 1)) = w; }
;             LRU_BAR();
;             if (sg + 1 < 4) LRU_LOAD_RAW(seg + 1)
.LBB0_225:
	s_or_b64 exec, exec, s[18:19]
	s_waitcnt lgkmcnt(0)
	s_barrier
	ds_read_b128 v[92:95], v155 offset:43008
	ds_read_b128 v[88:91], v155 offset:44032
	s_waitcnt lgkmcnt(6)
	ds_read_b128 v[84:87], v155 offset:45056
	s_waitcnt lgkmcnt(3)
	ds_read_b128 v[80:83], v155 offset:46080
	ds_read_b128 v[96:99], v155 offset:47104
	ds_read2_b64 v[114:117], v165 offset1:34
	v_add_u32_e32 v1, 0x1000, v165
	s_cmp_eq_u32 s0, 0x12000
	s_waitcnt lgkmcnt(0)
	v_lshlrev_b32_e32 v118, 16, v114
	v_and_b32_e32 v119, 0xffff0000, v114
	v_lshlrev_b32_e32 v114, 16, v115
	v_and_b32_e32 v115, 0xffff0000, v115
	v_pk_fma_f32 v[114:115], v[94:95], v[114:115], v[98:99]
	v_lshlrev_b32_e32 v120, 16, v116
	v_and_b32_e32 v121, 0xffff0000, v116
	v_lshlrev_b32_e32 v116, 16, v117
	v_and_b32_e32 v117, 0xffff0000, v117
	v_pk_fma_f32 v[122:123], v[90:91], v[116:117], v[114:115]
	ds_read2_b64 v[114:117], v165 offset0:68 offset1:102
	v_pk_fma_f32 v[118:119], v[92:93], v[118:119], v[96:97]
	s_nop 0
	v_pk_fma_f32 v[118:119], v[88:89], v[120:121], v[118:119]
	s_waitcnt lgkmcnt(0)
	v_lshlrev_b32_e32 v120, 16, v114
	v_and_b32_e32 v121, 0xffff0000, v114
	v_lshlrev_b32_e32 v114, 16, v115
	v_and_b32_e32 v115, 0xffff0000, v115
	v_pk_fma_f32 v[118:119], v[84:85], v[120:121], v[118:119]
	v_pk_fma_f32 v[114:115], v[86:87], v[114:115], v[122:123]
	v_lshlrev_b32_e32 v120, 16, v116
	v_and_b32_e32 v121, 0xffff0000, v116
	v_lshlrev_b32_e32 v116, 16, v117
	v_and_b32_e32 v117, 0xffff0000, v117
	v_pk_fma_f32 v[114:115], v[82:83], v[116:117], v[114:115]
	v_pk_fma_f32 v[116:117], v[80:81], v[120:121], v[118:119]
	v_mul_f32_e32 v232, s24, v114
	v_mul_f32_e32 v233, s24, v115
	v_mul_f32_e32 v234, s24, v116
	v_mul_f32_e32 v235, s24, v117
	v_cvt_pk_bf16_f32 v119, v232, v233
	v_cvt_pk_bf16_f32 v118, v234, v235
	ds_write_b64 v166, v[118:119] offset:18432
	ds_read2_b64 v[118:121], v1 offset0:32 offset1:66
	s_waitcnt lgkmcnt(0)
	v_lshlrev_b32_e32 v122, 16, v118
	v_and_b32_e32 v123, 0xffff0000, v118
	v_lshlrev_b32_e32 v118, 16, v119
	v_and_b32_e32 v119, 0xffff0000, v119
	v_pk_fma_f32 v[118:119], v[94:95], v[118:119], v[98:99]
	v_lshlrev_b32_e32 v124, 16, v120
	v_and_b32_e32 v125, 0xffff0000, v120
	v_lshlrev_b32_e32 v120, 16, v121
	v_and_b32_e32 v121, 0xffff0000, v121
	v_pk_fma_f32 v[126:127], v[90:91], v[120:121], v[118:119]
	ds_read2_b64 v[118:121], v1 offset0:100 offset1:134
	v_pk_fma_f32 v[122:123], v[92:93], v[122:123], v[96:97]
	v_add_u32_e32 v1, 0x2000, v165
	v_pk_fma_f32 v[122:123], v[88:89], v[124:125], v[122:123]
	s_waitcnt lgkmcnt(0)
	v_lshlrev_b32_e32 v124, 16, v118
	v_and_b32_e32 v125, 0xffff0000, v118
	v_lshlrev_b32_e32 v118, 16, v119
	v_and_b32_e32 v119, 0xffff0000, v119
	v_pk_fma_f32 v[122:123], v[84:85], v[124:125], v[122:123]
	v_pk_fma_f32 v[118:119], v[86:87], v[118:119], v[126:127]
	v_lshlrev_b32_e32 v124, 16, v120
	v_and_b32_e32 v125, 0xffff0000, v120
	v_lshlrev_b32_e32 v120, 16, v121
	v_and_b32_e32 v121, 0xffff0000, v121
	v_pk_fma_f32 v[118:119], v[82:83], v[120:121], v[118:119]
	v_pk_fma_f32 v[120:121], v[80:81], v[124:125], v[122:123]
	v_mul_f32_e32 v232, s24, v118
	v_mul_f32_e32 v233, s24, v119
	v_mul_f32_e32 v234, s24, v120
	v_mul_f32_e32 v235, s24, v121
	v_cvt_pk_bf16_f32 v123, v232, v233
	v_cvt_pk_bf16_f32 v122, v234, v235
	ds_write_b64 v166, v[122:123] offset:22528
	ds_read2_b64 v[122:125], v1 offset0:64 offset1:98
	s_waitcnt lgkmcnt(0)
	v_lshlrev_b32_e32 v126, 16, v122
	v_and_b32_e32 v127, 0xffff0000, v122
	v_lshlrev_b32_e32 v122, 16, v123
	v_and_b32_e32 v123, 0xffff0000, v123
	v_pk_fma_f32 v[122:123], v[94:95], v[122:123], v[98:99]
	v_lshlrev_b32_e32 v128, 16, v124
	v_and_b32_e32 v129, 0xffff0000, v124
	v_lshlrev_b32_e32 v124, 16, v125
	v_and_b32_e32 v125, 0xffff0000, v125
	v_pk_fma_f32 v[144:145], v[90:91], v[124:125], v[122:123]
	ds_read2_b64 v[122:125], v1 offset0:132 offset1:166
	v_pk_fma_f32 v[126:127], v[92:93], v[126:127], v[96:97]
	s_nop 0
	v_pk_fma_f32 v[126:127], v[88:89], v[128:129], v[126:127]
	s_waitcnt lgkmcnt(0)
	v_lshlrev_b32_e32 v128, 16, v122
	v_and_b32_e32 v129, 0xffff0000, v122
	v_lshlrev_b32_e32 v122, 16, v123
	v_and_b32_e32 v123, 0xffff0000, v123
	v_pk_fma_f32 v[126:127], v[84:85], v[128:129], v[126:127]
	v_pk_fma_f32 v[122:123], v[86:87], v[122:123], v[144:145]
	v_lshlrev_b32_e32 v128, 16, v124
	v_and_b32_e32 v129, 0xffff0000, v124
	v_lshlrev_b32_e32 v124, 16, v125
	v_and_b32_e32 v125, 0xffff0000, v125
	v_pk_fma_f32 v[122:123], v[82:83], v[124:125], v[122:123]
	v_pk_fma_f32 v[124:125], v[80:81], v[128:129], v[126:127]
	v_mul_f32_e32 v232, s24, v122
	v_mul_f32_e32 v233, s24, v123
	v_mul_f32_e32 v234, s24, v124
	v_mul_f32_e32 v235, s24, v125
	v_cvt_pk_bf16_f32 v127, v232, v233
	v_cvt_pk_bf16_f32 v126, v234, v235
	ds_write_b64 v166, v[126:127] offset:26624
	ds_read2_b64 v[126:129], v167 offset1:34
	s_waitcnt lgkmcnt(0)
	v_lshlrev_b32_e32 v144, 16, v126
	v_and_b32_e32 v145, 0xffff0000, v126
	v_lshlrev_b32_e32 v126, 16, v127
	v_and_b32_e32 v127, 0xffff0000, v127
	v_pk_fma_f32 v[92:93], v[92:93], v[144:145], v[96:97]
	v_pk_fma_f32 v[94:95], v[94:95], v[126:127], v[98:99]
	v_lshlrev_b32_e32 v96, 16, v128
	v_and_b32_e32 v97, 0xffff0000, v128
	v_lshlrev_b32_e32 v98, 16, v129
	v_and_b32_e32 v99, 0xffff0000, v129
	v_pk_fma_f32 v[94:95], v[90:91], v[98:99], v[94:95]
	v_pk_fma_f32 v[92:93], v[88:89], v[96:97], v[92:93]
	ds_read2_b64 v[88:91], v167 offset0:68 offset1:102
	s_waitcnt lgkmcnt(0)
	v_lshlrev_b32_e32 v96, 16, v88
	v_and_b32_e32 v97, 0xffff0000, v88
	v_lshlrev_b32_e32 v88, 16, v89
	v_and_b32_e32 v89, 0xffff0000, v89
	v_pk_fma_f32 v[84:85], v[84:85], v[96:97], v[92:93]
	v_pk_fma_f32 v[86:87], v[86:87], v[88:89], v[94:95]
	v_lshlrev_b32_e32 v88, 16, v90
	v_and_b32_e32 v89, 0xffff0000, v90
	v_lshlrev_b32_e32 v90, 16, v91
	v_and_b32_e32 v91, 0xffff0000, v91
	v_pk_fma_f32 v[126:127], v[82:83], v[90:91], v[86:87]
	v_pk_fma_f32 v[128:129], v[80:81], v[88:89], v[84:85]
	v_mul_f32_e32 v232, s24, v126
	v_mul_f32_e32 v233, s24, v127
	v_mul_f32_e32 v234, s24, v128
	v_mul_f32_e32 v235, s24, v129
	v_cvt_pk_bf16_f32 v81, v232, v233
	v_cvt_pk_bf16_f32 v80, v234, v235
	ds_write_b64 v166, v[80:81] offset:30720
	s_waitcnt lgkmcnt(0)
	s_barrier
	s_cbranch_scc1 .LBB0_233
	s_and_b32 s34, s28, s30
	s_add_i32 s34, s34, -2
	v_add_u32_e32 v1, s34, v156
	s_waitcnt vmcnt(0)
	v_mov_b32_e32 v72, 0
	v_mov_b32_e32 v73, v0
	v_cmp_gt_u32_e32 vcc, s62, v1
	v_mov_b32_e32 v74, v0
	v_mov_b32_e32 v75, v0
	v_mov_b64_e32 v[68:69], v[72:73]
	s_and_b64 s[58:59], s[42:43], vcc
	v_mov_b64_e32 v[70:71], v[74:75]
	s_and_saveexec_b64 s[18:19], s[58:59]
	s_cbranch_execz .LBB0_228
	v_lshl_add_u64 v[68:69], s[88:89], 0, v[108:109]
	global_load_dwordx4 v[68:71], v[68:69], off

; #define LAS __attribute__((address_space(3)))
; template <int PASS> __device__ __forceinline__ void phase_lru(LAS unsigned char* lds, const bf16_t* Z, const bf16_t* WL, float* LSUM, const float* LCAR, bf16_t* RNN,
;                                                               int S, int tid, int lane, int wave, int G) {
;     ...
;                 for (int t = 0; t < 4; ++t) {
;                     f32x4 gr = (f32x4){0.f, 0.f, 0.f, 0.f}, gi = gr;
; #pragma unroll
;                     for (int s = 0; s < 4; ++s) { const bf16x8 bfr = *(const LAS bf16x8*)(lds + LRU_XC + off_b(16 * t + c, 4 * s + g4));
;                         gr = __builtin_amdgcn_mfma_f32_16x16x32_bf16(wf[0][s], bfr, gr, 0, 0, 0); gi = __builtin_amdgcn_mfma_f32_16x16x32_bf16(wf[1][s], bfr, gi, 0, 0, 0); }
;                     const f32x4 kba = kc[0 * 64 + lane], kbx = kc[1 * 64 + lane], ksp = kc[2 * 64 + lane];
;                     f32x4 av, hv;
; #pragma unroll
;                     for (int j = 0; j < 4; ++j) {
;                         const float rg = __builtin_amdgcn_rcpf(1.0f + __builtin_amdgcn_exp2f(fmaf(gr[j], -LOG2E, kba[j])));
;                         const float ig = __builtin_amdgcn_rcpf(1.0f + __builtin_amdgcn_exp2f(fmaf(gi[j], -LOG2E, kbx[j])));
;                         const float a_ = __builtin_amdgcn_exp2f(rg * ksp[j]);
;                         av[j] = a_; hv[j] = __builtin_amdgcn_sqrtf(fmaf(-a_, a_, 1.0f)) * (ig * xc[t][j]);
;                     }
;                     lru_scan4_fwd(av, hv);
; #pragma unroll
;                     for (int j = 0; j < 4; ++j) {
;                         const float hfull = fmaf(av[j], Hc[j], hv[j]);
;                         if (PASS == 1) hf[t][j] = hfull;
;                         Hc[j] = __shfl(hfull, (lane & 48) | 15);
;                         if (PASS == 0) Ac[j] *= __shfl(av[j], (lane & 48) | 15);
;                     }
;                     __builtin_amdgcn_sched_barrier(0);
.LBB0_233:
	ds_read_b128 v[220:223], v155 offset:36864
	ds_read_b128 v[224:227], v155 offset:37888
	ds_read_b128 v[228:231], v155 offset:38912
	ds_read_b128 v[204:207], v169 offset:18432
	ds_read_b128 v[208:211], v170 offset:18432
	ds_read_b128 v[212:215], v172 offset:18432
	ds_read_b128 v[216:219], v171 offset:18432
	s_waitcnt lgkmcnt(0)
	v_mfma_f32_16x16x32_bf16 v[236:239], v[4:7], v[204:207], v[220:223]
	v_mfma_f32_16x16x32_bf16 v[240:243], v[20:23], v[204:207], v[224:227]
	v_mfma_f32_16x16x32_bf16 v[236:239], v[8:11], v[208:211], v[236:239]
	v_mfma_f32_16x16x32_bf16 v[240:243], v[24:27], v[208:211], v[240:243]
	v_mfma_f32_16x16x32_bf16 v[236:239], v[12:15], v[216:219], v[236:239]
	v_mfma_f32_16x16x32_bf16 v[240:243], v[28:31], v[216:219], v[240:243]
	v_mfma_f32_16x16x32_bf16 v[236:239], v[16:19], v[212:215], v[236:239]
	v_mfma_f32_16x16x32_bf16 v[240:243], v[32:35], v[212:215], v[240:243]
	s_nop 7
	s_nop 1
	v_exp_f32_e32 v1, v236
	v_exp_f32_e32 v80, v240
	v_add_f32_e32 v1, 1.0, v1
	v_rcp_f32_e32 v1, v1
	v_add_f32_e32 v80, 1.0, v80
	v_rcp_f32_e32 v80, v80
	v_exp_f32_e32 v81, v241
	v_mul_f32_e32 v1, v228, v1
	v_exp_f32_e32 v1, v1
	v_mul_f32_e32 v80, v116, v80
	v_add_f32_e32 v81, 1.0, v81
	v_rcp_f32_e32 v81, v81
	v_fma_f32 v84, -v1, v1, 1.0
	v_sqrt_f32_e32 v84, v84
	v_mul_f32_e32 v81, v117, v81
	v_exp_f32_e32 v82, v242
	v_mul_f32_e32 v80, v80, v84
	v_exp_f32_e32 v84, v237
	v_add_f32_e32 v82, 1.0, v82
	v_rcp_f32_e32 v82, v82
	v_add_f32_e32 v84, 1.0, v84
	v_rcp_f32_e32 v84, v84
	v_mul_f32_e32 v82, v114, v82
	v_exp_f32_e32 v83, v243
	ds_read_b128 v[204:207], v169 offset:22528
	ds_read_b128 v[208:211], v170 offset:22528
	ds_read_b128 v[212:215], v172 offset:22528
	ds_read_b128 v[216:219], v171 offset:22528
	v_mul_f32_e32 v84, v229, v84
	v_exp_f32_e32 v84, v84
	v_add_f32_e32 v83, 1.0, v83
	v_rcp_f32_e32 v83, v83
	v_fma_f32 v85, -v84, v84, 1.0
	v_sqrt_f32_e32 v85, v85
	v_mul_f32_e32 v83, v115, v83
	v_mul_f32_e32 v81, v81, v85
	v_exp_f32_e32 v85, v238
	s_nop 0
	v_add_f32_e32 v85, 1.0, v85
	v_rcp_f32_e32 v85, v85
	s_nop 0
	v_mul_f32_e32 v85, v230, v85
	v_exp_f32_e32 v85, v85
	s_nop 0
	v_fma_f32 v86, -v85, v85, 1.0
	v_sqrt_f32_e32 v86, v86
	s_nop 0
	v_mul_f32_e32 v82, v82, v86
	v_exp_f32_e32 v86, v239
	s_nop 0
	v_add_f32_e32 v86, 1.0, v86
	v_rcp_f32_e32 v86, v86
	s_nop 0
	v_mul_f32_e32 v86, v231, v86
	v_exp_f32_e32 v86, v86
	s_nop 0
	v_fma_f32 v87, -v86, v86, 1.0
	v_sqrt_f32_e32 v87, v87
	s_nop 0
	v_mul_f32_e32 v83, v83, v87
	s_waitcnt lgkmcnt(0)
	v_mfma_f32_16x16x32_bf16 v[236:239], v[4:7], v[204:207], v[220:223]
	v_mfma_f32_16x16x32_bf16 v[240:243], v[20:23], v[204:207], v[224:227]
	v_mfma_f32_16x16x32_bf16 v[236:239], v[8:11], v[208:211], v[236:239]
	v_mfma_f32_16x16x32_bf16 v[240:243], v[24:27], v[208:211], v[240:243]
	v_mfma_f32_16x16x32_bf16 v[236:239], v[12:15], v[216:219], v[236:239]
	v_mfma_f32_16x16x32_bf16 v[240:243], v[28:31], v[216:219], v[240:243]
	v_mfma_f32_16x16x32_bf16 v[236:239], v[16:19], v[212:215], v[236:239]
	v_mfma_f32_16x16x32_bf16 v[240:243], v[32:35], v[212:215], v[240:243]
	s_nop 1
	v_fmac_f32_dpp v80, v80, v1 row_shr:1 row_mask:0xf bank_mask:0xf
	v_fmac_f32_dpp v81, v81, v84 row_shr:1 row_mask:0xf bank_mask:0xf
	v_fmac_f32_dpp v82, v82, v85 row_shr:1 row_mask:0xf bank_mask:0xf
	v_fmac_f32_dpp v83, v83, v86 row_shr:1 row_mask:0xf bank_mask:0xf
	v_mul_f32_dpp v1, v1, v1 row_shr:1 row_mask:0xf bank_mask:0xf
	v_mul_f32_dpp v84, v84, v84 row_shr:1 row_mask:0xf bank_mask:0xf
	v_mul_f32_dpp v85, v85, v85 row_shr:1 row_mask:0xf bank_mask:0xf
	v_mul_f32_dpp v86, v86, v86 row_shr:1 row_mask:0xf bank_mask:0xf
	v_fmac_f32_dpp v80, v80, v1 row_shr:2 row_mask:0xf bank_mask:0xf
	v_fmac_f32_dpp v81, v81, v84 row_shr:2 row_mask:0xf bank_mask:0xf
	v_fmac_f32_dpp v82, v82, v85 row_shr:2 row_mask:0xf bank_mask:0xf
	v_fmac_f32_dpp v83, v83, v86 row_shr:2 row_mask:0xf bank_mask:0xf
	v_mul_f32_dpp v1, v1, v1 row_shr:2 row_mask:0xf bank_mask:0xf
	v_mul_f32_dpp v84, v84, v84 row_shr:2 row_mask:0xf bank_mask:0xf
	v_mul_f32_dpp v85, v85, v85 row_shr:2 row_mask:0xf bank_mask:0xf
	v_mul_f32_dpp v86, v86, v86 row_shr:2 row_mask:0xf bank_mask:0xf
	v_fmac_f32_dpp v80, v80, v1 row_shr:4 row_mask:0xf bank_mask:0xf
	v_fmac_f32_dpp v81, v81, v84 row_shr:4 row_mask:0xf bank_mask:0xf
	v_fmac_f32_dpp v82, v82, v85 row_shr:4 row_mask:0xf bank_mask:0xf
	v_fmac_f32_dpp v83, v83, v86 row_shr:4 row_mask:0xf bank_mask:0xf
	v_mul_f32_dpp v1, v1, v1 row_shr:4 row_mask:0xf bank_mask:0xf
	v_mul_f32_dpp v84, v84, v84 row_shr:4 row_mask:0xf bank_mask:0xf
	v_mul_f32_dpp v85, v85, v85 row_shr:4 row_mask:0xf bank_mask:0xf
	v_mul_f32_dpp v86, v86, v86 row_shr:4 row_mask:0xf bank_mask:0xf
	v_fmac_f32_dpp v80, v80, v1 row_shr:8 row_mask:0xf bank_mask:0xf
	v_fmac_f32_dpp v81, v81, v84 row_shr:8 row_mask:0xf bank_mask:0xf
	v_fmac_f32_dpp v82, v82, v85 row_shr:8 row_mask:0xf bank_mask:0xf
	v_fmac_f32_dpp v83, v83, v86 row_shr:8 row_mask:0xf bank_mask:0xf
	v_mul_f32_dpp v1, v1, v1 row_shr:8 row_mask:0xf bank_mask:0xf
	v_mul_f32_dpp v84, v84, v84 row_shr:8 row_mask:0xf bank_mask:0xf
	v_mul_f32_dpp v85, v85, v85 row_shr:8 row_mask:0xf bank_mask:0xf
	v_mul_f32_dpp v86, v86, v86 row_shr:8 row_mask:0xf bank_mask:0xf
	s_nop 1
	v_or_b32_e32 v87, v193, v202
	v_lshl_or_b32 v144, v87, 2, 60
	v_fmac_f32_e32 v80, 0, v1
	v_fmac_f32_e32 v81, 0, v84
	v_fmac_f32_e32 v82, 0, v85
	v_fmac_f32_e32 v83, 0, v86
	v_mov_b32_dpp v145, v80 row_newbcast:15 row_mask:0xf bank_mask:0xf
	v_mov_b32_dpp v1, v1 row_newbcast:15 row_mask:0xf bank_mask:0xf
	v_mov_b32_dpp v146, v81 row_newbcast:15 row_mask:0xf bank_mask:0xf
	v_mov_b32_dpp v173, v84 row_newbcast:15 row_mask:0xf bank_mask:0xf
; #define LAS __attribute__((address_space(3)))
; template <int PASS> __device__ __forceinline__ void phase_lru(LAS unsigned char* lds, const bf16_t* Z, const bf16_t* WL, float* LSUM, const float* LCAR, bf16_t* RNN,
;                                                               int S, int tid, int lane, int wave, int G) {
;     ...
;                 for (int t = 0; t < 4; ++t) {
;                     f32x4 gr = (f32x4){0.f, 0.f, 0.f, 0.f}, gi = gr;
; #pragma unroll
;                     for (int s = 0; s < 4; ++s) { const bf16x8 bfr = *(const LAS bf16x8*)(lds + LRU_XC + off_b(16 * t + c, 4 * s + g4));
;                         gr = __builtin_amdgcn_mfma_f32_16x16x32_bf16(wf[0][s], bfr, gr, 0, 0, 0); gi = __builtin_amdgcn_mfma_f32_16x16x32_bf16(wf[1][s], bfr, gi, 0, 0, 0); }
;                     const f32x4 kba = kc[0 * 64 + lane], kbx = kc[1 * 64 + lane], ksp = kc[2 * 64 + lane];
;                     f32x4 av, hv;
; #pragma unroll
;                     for (int j = 0; j < 4; ++j) {
;                         const float rg = __builtin_amdgcn_rcpf(1.0f + __builtin_amdgcn_exp2f(fmaf(gr[j], -LOG2E, kba[j])));
;                         const float ig = __builtin_amdgcn_rcpf(1.0f + __builtin_amdgcn_exp2f(fmaf(gi[j], -LOG2E, kbx[j])));
;                         const float a_ = __builtin_amdgcn_exp2f(rg * ksp[j]);
;                         av[j] = a_; hv[j] = __builtin_amdgcn_sqrtf(fmaf(-a_, a_, 1.0f)) * (ig * xc[t][j]);
;                     }
;                     lru_scan4_fwd(av, hv);
; #pragma unroll
;                     for (int j = 0; j < 4; ++j) {
;                         const float hfull = fmaf(av[j], Hc[j], hv[j]);
;                         if (PASS == 1) hf[t][j] = hfull;
;                         Hc[j] = __shfl(hfull, (lane & 48) | 15);
;                         if (PASS == 0) Ac[j] *= __shfl(av[j], (lane & 48) | 15);
;                     }
;                     __builtin_amdgcn_sched_barrier(0);
	v_mov_b32_dpp v147, v82 row_newbcast:15 row_mask:0xf bank_mask:0xf
	v_mov_b32_dpp v174, v85 row_newbcast:15 row_mask:0xf bank_mask:0xf
	v_mov_b32_dpp v179, v83 row_newbcast:15 row_mask:0xf bank_mask:0xf
	v_mov_b32_dpp v175, v86 row_newbcast:15 row_mask:0xf bank_mask:0xf
	v_exp_f32_e32 v88, v236
	v_exp_f32_e32 v80, v240
	v_add_f32_e32 v88, 1.0, v88
	v_rcp_f32_e32 v88, v88
	v_add_f32_e32 v80, 1.0, v80
	v_rcp_f32_e32 v80, v80
	v_exp_f32_e32 v81, v241
	v_mul_f32_e32 v84, v228, v88
	v_exp_f32_e32 v84, v84
	v_mul_f32_e32 v80, v120, v80
	v_add_f32_e32 v81, 1.0, v81
	v_rcp_f32_e32 v81, v81
	v_fma_f32 v88, -v84, v84, 1.0
	v_sqrt_f32_e32 v88, v88
	v_mul_f32_e32 v81, v121, v81
	v_exp_f32_e32 v82, v242
	v_mul_f32_e32 v80, v80, v88
	v_exp_f32_e32 v88, v237
	v_add_f32_e32 v82, 1.0, v82
	v_rcp_f32_e32 v82, v82
	v_add_f32_e32 v88, 1.0, v88
	v_rcp_f32_e32 v88, v88
	v_mul_f32_e32 v82, v118, v82
	v_exp_f32_e32 v83, v243
	ds_read_b128 v[204:207], v169 offset:26624
	ds_read_b128 v[208:211], v170 offset:26624
	ds_read_b128 v[212:215], v172 offset:26624
	ds_read_b128 v[216:219], v171 offset:26624
	v_mul_f32_e32 v85, v229, v88
	v_exp_f32_e32 v85, v85
	v_add_f32_e32 v83, 1.0, v83
	v_rcp_f32_e32 v83, v83
	v_fma_f32 v88, -v85, v85, 1.0
	v_sqrt_f32_e32 v88, v88
	v_mul_f32_e32 v83, v119, v83
	v_mul_f32_e32 v81, v81, v88
	v_exp_f32_e32 v88, v238
	s_nop 0
	v_add_f32_e32 v88, 1.0, v88
	v_rcp_f32_e32 v88, v88
	s_nop 0
	v_mul_f32_e32 v86, v230, v88
	v_exp_f32_e32 v86, v86
	s_nop 0
	v_fma_f32 v88, -v86, v86, 1.0
	v_sqrt_f32_e32 v88, v88
	s_nop 0
	v_mul_f32_e32 v82, v82, v88
	v_exp_f32_e32 v88, v239
	s_nop 0
	v_add_f32_e32 v88, 1.0, v88
	v_rcp_f32_e32 v88, v88
	s_nop 0
	v_mul_f32_e32 v87, v231, v88
	v_exp_f32_e32 v87, v87
	s_nop 0
	v_fma_f32 v88, -v87, v87, 1.0
	v_sqrt_f32_e32 v88, v88
	s_nop 0
	v_mul_f32_e32 v83, v83, v88
	s_waitcnt lgkmcnt(0)
	v_mfma_f32_16x16x32_bf16 v[236:239], v[4:7], v[204:207], v[220:223]
	v_mfma_f32_16x16x32_bf16 v[240:243], v[20:23], v[204:207], v[224:227]
	v_mfma_f32_16x16x32_bf16 v[236:239], v[8:11], v[208:211], v[236:239]
	v_mfma_f32_16x16x32_bf16 v[240:243], v[24:27], v[208:211], v[240:243]
	v_mfma_f32_16x16x32_bf16 v[236:239], v[12:15], v[216:219], v[236:239]
	v_mfma_f32_16x16x32_bf16 v[240:243], v[28:31], v[216:219], v[240:243]
	v_mfma_f32_16x16x32_bf16 v[236:239], v[16:19], v[212:215], v[236:239]
	v_mfma_f32_16x16x32_bf16 v[240:243], v[32:35], v[212:215], v[240:243]
	s_nop 1
	v_fmac_f32_dpp v80, v80, v84 row_shr:1 row_mask:0xf bank_mask:0xf
	v_fmac_f32_dpp v81, v81, v85 row_shr:1 row_mask:0xf bank_mask:0xf
	v_fmac_f32_dpp v82, v82, v86 row_shr:1 row_mask:0xf bank_mask:0xf
	v_fmac_f32_dpp v83, v83, v87 row_shr:1 row_mask:0xf bank_mask:0xf
	v_mul_f32_dpp v84, v84, v84 row_shr:1 row_mask:0xf bank_mask:0xf
	v_mul_f32_dpp v85, v85, v85 row_shr:1 row_mask:0xf bank_mask:0xf
	v_mul_f32_dpp v86, v86, v86 row_shr:1 row_mask:0xf bank_mask:0xf
	v_mul_f32_dpp v87, v87, v87 row_shr:1 row_mask:0xf bank_mask:0xf
	v_fmac_f32_dpp v80, v80, v84 row_shr:2 row_mask:0xf bank_mask:0xf
	v_fmac_f32_dpp v81, v81, v85 row_shr:2 row_mask:0xf bank_mask:0xf
	v_fmac_f32_dpp v82, v82, v86 row_shr:2 row_mask:0xf bank_mask:0xf
	v_fmac_f32_dpp v83, v83, v87 row_shr:2 row_mask:0xf bank_mask:0xf
	v_mul_f32_dpp v84, v84, v84 row_shr:2 row_mask:0xf bank_mask:0xf
	v_mul_f32_dpp v85, v85, v85 row_shr:2 row_mask:0xf bank_mask:0xf
	v_mul_f32_dpp v86, v86, v86 row_shr:2 row_mask:0xf bank_mask:0xf
	v_mul_f32_dpp v87, v87, v87 row_shr:2 row_mask:0xf bank_mask:0xf
	v_fmac_f32_dpp v80, v80, v84 row_shr:4 row_mask:0xf bank_mask:0xf
	v_fmac_f32_dpp v81, v81, v85 row_shr:4 row_mask:0xf bank_mask:0xf
	v_fmac_f32_dpp v82, v82, v86 row_shr:4 row_mask:0xf bank_mask:0xf
	v_fmac_f32_dpp v83, v83, v87 row_shr:4 row_mask:0xf bank_mask:0xf
	v_mul_f32_dpp v84, v84, v84 row_shr:4 row_mask:0xf bank_mask:0xf
	v_mul_f32_dpp v85, v85, v85 row_shr:4 row_mask:0xf bank_mask:0xf
	v_mul_f32_dpp v86, v86, v86 row_shr:4 row_mask:0xf bank_mask:0xf
	v_mul_f32_dpp v87, v87, v87 row_shr:4 row_mask:0xf bank_mask:0xf
	v_fmac_f32_dpp v80, v80, v84 row_shr:8 row_mask:0xf bank_mask:0xf
	v_fmac_f32_dpp v81, v81, v85 row_shr:8 row_mask:0xf bank_mask:0xf
	v_fmac_f32_dpp v82, v82, v86 row_shr:8 row_mask:0xf bank_mask:0xf
	v_fmac_f32_dpp v83, v83, v87 row_shr:8 row_mask:0xf bank_mask:0xf
	v_mul_f32_dpp v84, v84, v84 row_shr:8 row_mask:0xf bank_mask:0xf
	v_mul_f32_dpp v85, v85, v85 row_shr:8 row_mask:0xf bank_mask:0xf
	v_mul_f32_dpp v86, v86, v86 row_shr:8 row_mask:0xf bank_mask:0xf
	v_mul_f32_dpp v87, v87, v87 row_shr:8 row_mask:0xf bank_mask:0xf
	s_nop 1
	v_mov_b32_dpp v176, v84 row_newbcast:15 row_mask:0xf bank_mask:0xf
	v_fmac_f32_e32 v80, v84, v145
	v_fmac_f32_e32 v81, v85, v146
	v_fmac_f32_e32 v82, v86, v147
	v_fmac_f32_e32 v83, v87, v179
	v_mov_b32_dpp v145, v80 row_newbcast:15 row_mask:0xf bank_mask:0xf
	v_mov_b32_dpp v146, v81 row_newbcast:15 row_mask:0xf bank_mask:0xf
	v_mov_b32_dpp v177, v85 row_newbcast:15 row_mask:0xf bank_mask:0xf
	v_mov_b32_dpp v147, v82 row_newbcast:15 row_mask:0xf bank_mask:0xf
	v_mov_b32_dpp v178, v86 row_newbcast:15 row_mask:0xf bank_mask:0xf
	v_mov_b32_dpp v183, v83 row_newbcast:15 row_mask:0xf bank_mask:0xf
	v_mov_b32_dpp v179, v87 row_newbcast:15 row_mask:0xf bank_mask:0xf
	v_exp_f32_e32 v88, v236
	v_exp_f32_e32 v80, v240
	v_add_f32_e32 v88, 1.0, v88
	v_rcp_f32_e32 v88, v88
	v_add_f32_e32 v80, 1.0, v80
	v_rcp_f32_e32 v80, v80
	v_exp_f32_e32 v81, v241
	v_mul_f32_e32 v84, v228, v88
	v_exp_f32_e32 v84, v84
	v_mul_f32_e32 v80, v124, v80
	v_add_f32_e32 v81, 1.0, v81
	v_rcp_f32_e32 v81, v81
	v_fma_f32 v88, -v84, v84, 1.0
	v_sqrt_f32_e32 v88, v88
	v_mul_f32_e32 v81, v125, v81
	v_exp_f32_e32 v82, v242
	v_mul_f32_e32 v80, v80, v88
	v_exp_f32_e32 v88, v237
	v_add_f32_e32 v82, 1.0, v82
	v_rcp_f32_e32 v82, v82
	v_add_f32_e32 v88, 1.0, v88
	v_rcp_f32_e32 v88, v88
	v_mul_f32_e32 v82, v122, v82
	v_exp_f32_e32 v83, v243
	ds_read_b128 v[204:207], v169 offset:30720
	ds_read_b128 v[208:211], v170 offset:30720
	ds_read_b128 v[212:215], v172 offset:30720
	ds_read_b128 v[216:219], v171 offset:30720
	v_mul_f32_e32 v85, v229, v88
	v_exp_f32_e32 v85, v85
	v_add_f32_e32 v83, 1.0, v83
	v_rcp_f32_e32 v83, v83
	v_fma_f32 v88, -v85, v85, 1.0
	v_sqrt_f32_e32 v88, v88
	v_mul_f32_e32 v83, v123, v83
	v_mul_f32_e32 v81, v81, v88
	v_exp_f32_e32 v88, v238
	s_nop 0
	v_add_f32_e32 v88, 1.0, v88
	v_rcp_f32_e32 v88, v88
	s_nop 0
	v_mul_f32_e32 v86, v230, v88
	v_exp_f32_e32 v86, v86
	s_nop 0
	v_fma_f32 v88, -v86, v86, 1.0
	v_sqrt_f32_e32 v88, v88
	s_nop 0
	v_mul_f32_e32 v82, v82, v88
	v_exp_f32_e32 v88, v239
	s_nop 0
	v_add_f32_e32 v88, 1.0, v88
	v_rcp_f32_e32 v88, v88
	s_nop 0
	v_mul_f32_e32 v87, v231, v88
	v_exp_f32_e32 v87, v87
	s_nop 0
	v_fma_f32 v88, -v87, v87, 1.0
	v_sqrt_f32_e32 v88, v88
	s_nop 0
	v_mul_f32_e32 v83, v83, v88
	s_waitcnt lgkmcnt(0)
; #define LAS __attribute__((address_space(3)))
; template <int PASS> __device__ __forceinline__ void phase_lru(LAS unsigned char* lds, const bf16_t* Z, const bf16_t* WL, float* LSUM, const float* LCAR, bf16_t* RNN,
;                                                               int S, int tid, int lane, int wave, int G) {
;     ...
;                 for (int t = 0; t < 4; ++t) {
;                     f32x4 gr = (f32x4){0.f, 0.f, 0.f, 0.f}, gi = gr;
; #pragma unroll
;                     for (int s = 0; s < 4; ++s) { const bf16x8 bfr = *(const LAS bf16x8*)(lds + LRU_XC + off_b(16 * t + c, 4 * s + g4));
;                         gr = __builtin_amdgcn_mfma_f32_16x16x32_bf16(wf[0][s], bfr, gr, 0, 0, 0); gi = __builtin_amdgcn_mfma_f32_16x16x32_bf16(wf[1][s], bfr, gi, 0, 0, 0); }
;                     const f32x4 kba = kc[0 * 64 + lane], kbx = kc[1 * 64 + lane], ksp = kc[2 * 64 + lane];
;                     f32x4 av, hv;
; #pragma unroll
;                     for (int j = 0; j < 4; ++j) {
;                         const float rg = __builtin_amdgcn_rcpf(1.0f + __builtin_amdgcn_exp2f(fmaf(gr[j], -LOG2E, kba[j])));
;                         const float ig = __builtin_amdgcn_rcpf(1.0f + __builtin_amdgcn_exp2f(fmaf(gi[j], -LOG2E, kbx[j])));
;                         const float a_ = __builtin_amdgcn_exp2f(rg * ksp[j]);
;                         av[j] = a_; hv[j] = __builtin_amdgcn_sqrtf(fmaf(-a_, a_, 1.0f)) * (ig * xc[t][j]);
;                     }
;                     lru_scan4_fwd(av, hv);
; #pragma unroll
;                     for (int j = 0; j < 4; ++j) {
;                         const float hfull = fmaf(av[j], Hc[j], hv[j]);
;                         if (PASS == 1) hf[t][j] = hfull;
;                         Hc[j] = __shfl(hfull, (lane & 48) | 15);
;                         if (PASS == 0) Ac[j] *= __shfl(av[j], (lane & 48) | 15);
;                     }
;                     __builtin_amdgcn_sched_barrier(0);
	v_mfma_f32_16x16x32_bf16 v[236:239], v[4:7], v[204:207], v[220:223]
	v_mfma_f32_16x16x32_bf16 v[240:243], v[20:23], v[204:207], v[224:227]
	v_mfma_f32_16x16x32_bf16 v[236:239], v[8:11], v[208:211], v[236:239]
	v_mfma_f32_16x16x32_bf16 v[240:243], v[24:27], v[208:211], v[240:243]
	v_mfma_f32_16x16x32_bf16 v[236:239], v[12:15], v[216:219], v[236:239]
	v_mfma_f32_16x16x32_bf16 v[240:243], v[28:31], v[216:219], v[240:243]
	v_mfma_f32_16x16x32_bf16 v[236:239], v[16:19], v[212:215], v[236:239]
	v_mfma_f32_16x16x32_bf16 v[240:243], v[32:35], v[212:215], v[240:243]
	s_nop 1
	v_fmac_f32_dpp v80, v80, v84 row_shr:1 row_mask:0xf bank_mask:0xf
	v_fmac_f32_dpp v81, v81, v85 row_shr:1 row_mask:0xf bank_mask:0xf
	v_fmac_f32_dpp v82, v82, v86 row_shr:1 row_mask:0xf bank_mask:0xf
	v_fmac_f32_dpp v83, v83, v87 row_shr:1 row_mask:0xf bank_mask:0xf
	v_mul_f32_dpp v84, v84, v84 row_shr:1 row_mask:0xf bank_mask:0xf
	v_mul_f32_dpp v85, v85, v85 row_shr:1 row_mask:0xf bank_mask:0xf
	v_mul_f32_dpp v86, v86, v86 row_shr:1 row_mask:0xf bank_mask:0xf
	v_mul_f32_dpp v87, v87, v87 row_shr:1 row_mask:0xf bank_mask:0xf
	v_fmac_f32_dpp v80, v80, v84 row_shr:2 row_mask:0xf bank_mask:0xf
	v_fmac_f32_dpp v81, v81, v85 row_shr:2 row_mask:0xf bank_mask:0xf
	v_fmac_f32_dpp v82, v82, v86 row_shr:2 row_mask:0xf bank_mask:0xf
	v_fmac_f32_dpp v83, v83, v87 row_shr:2 row_mask:0xf bank_mask:0xf
	v_mul_f32_dpp v84, v84, v84 row_shr:2 row_mask:0xf bank_mask:0xf
	v_mul_f32_dpp v85, v85, v85 row_shr:2 row_mask:0xf bank_mask:0xf
	v_mul_f32_dpp v86, v86, v86 row_shr:2 row_mask:0xf bank_mask:0xf
	v_mul_f32_dpp v87, v87, v87 row_shr:2 row_mask:0xf bank_mask:0xf
	v_fmac_f32_dpp v80, v80, v84 row_shr:4 row_mask:0xf bank_mask:0xf
	v_fmac_f32_dpp v81, v81, v85 row_shr:4 row_mask:0xf bank_mask:0xf
	v_fmac_f32_dpp v82, v82, v86 row_shr:4 row_mask:0xf bank_mask:0xf
	v_fmac_f32_dpp v83, v83, v87 row_shr:4 row_mask:0xf bank_mask:0xf
	v_mul_f32_dpp v84, v84, v84 row_shr:4 row_mask:0xf bank_mask:0xf
	v_mul_f32_dpp v85, v85, v85 row_shr:4 row_mask:0xf bank_mask:0xf
	v_mul_f32_dpp v86, v86, v86 row_shr:4 row_mask:0xf bank_mask:0xf
	v_mul_f32_dpp v87, v87, v87 row_shr:4 row_mask:0xf bank_mask:0xf
	v_fmac_f32_dpp v80, v80, v84 row_shr:8 row_mask:0xf bank_mask:0xf
	v_fmac_f32_dpp v81, v81, v85 row_shr:8 row_mask:0xf bank_mask:0xf
	v_fmac_f32_dpp v82, v82, v86 row_shr:8 row_mask:0xf bank_mask:0xf
	v_fmac_f32_dpp v83, v83, v87 row_shr:8 row_mask:0xf bank_mask:0xf
	v_mul_f32_dpp v84, v84, v84 row_shr:8 row_mask:0xf bank_mask:0xf
	v_mul_f32_dpp v85, v85, v85 row_shr:8 row_mask:0xf bank_mask:0xf
	v_mul_f32_dpp v86, v86, v86 row_shr:8 row_mask:0xf bank_mask:0xf
	v_mul_f32_dpp v87, v87, v87 row_shr:8 row_mask:0xf bank_mask:0xf
	s_nop 1
	v_mov_b32_dpp v180, v84 row_newbcast:15 row_mask:0xf bank_mask:0xf
	v_fmac_f32_e32 v80, v84, v145
	v_fmac_f32_e32 v81, v85, v146
	v_fmac_f32_e32 v82, v86, v147
	v_mov_b32_dpp v145, v80 row_newbcast:15 row_mask:0xf bank_mask:0xf
	v_mov_b32_dpp v146, v81 row_newbcast:15 row_mask:0xf bank_mask:0xf
	v_mov_b32_dpp v181, v85 row_newbcast:15 row_mask:0xf bank_mask:0xf
	v_mov_b32_dpp v147, v82 row_newbcast:15 row_mask:0xf bank_mask:0xf
	v_mov_b32_dpp v182, v86 row_newbcast:15 row_mask:0xf bank_mask:0xf
	v_fmac_f32_e32 v83, v87, v183
	v_mov_b32_dpp v183, v87 row_newbcast:15 row_mask:0xf bank_mask:0xf
	s_nop 1
	v_mov_b32_dpp v184, v83 row_newbcast:15 row_mask:0xf bank_mask:0xf
	v_exp_f32_e32 v88, v236
	v_exp_f32_e32 v80, v240
	v_add_f32_e32 v88, 1.0, v88
	v_rcp_f32_e32 v88, v88
	v_add_f32_e32 v80, 1.0, v80
	v_rcp_f32_e32 v80, v80
	v_exp_f32_e32 v81, v241
	v_mul_f32_e32 v84, v228, v88
	v_exp_f32_e32 v84, v84
	v_mul_f32_e32 v80, v128, v80
	v_add_f32_e32 v81, 1.0, v81
	v_rcp_f32_e32 v81, v81
	v_fma_f32 v88, -v84, v84, 1.0
	v_sqrt_f32_e32 v88, v88
	v_mul_f32_e32 v81, v129, v81
	v_exp_f32_e32 v82, v242
	v_mul_f32_e32 v80, v80, v88
	v_exp_f32_e32 v88, v237
	v_add_f32_e32 v82, 1.0, v82
	v_rcp_f32_e32 v82, v82
	v_add_f32_e32 v88, 1.0, v88
	v_rcp_f32_e32 v88, v88
	v_mul_f32_e32 v82, v126, v82
	v_exp_f32_e32 v83, v243
	v_mul_f32_e32 v85, v229, v88
	v_exp_f32_e32 v88, v85
	v_add_f32_e32 v83, 1.0, v83
	v_rcp_f32_e32 v83, v83
	v_fma_f32 v85, -v88, v88, 1.0
	v_sqrt_f32_e32 v85, v85
	v_mul_f32_e32 v83, v127, v83
	v_mul_f32_e32 v81, v81, v85
	v_exp_f32_e32 v85, v238
	s_nop 0
	v_add_f32_e32 v85, 1.0, v85
	v_rcp_f32_e32 v85, v85
	s_nop 0
	v_mul_f32_e32 v85, v230, v85
	v_exp_f32_e32 v89, v85
	s_nop 0
	v_fma_f32 v85, -v89, v89, 1.0
	v_sqrt_f32_e32 v85, v85
	s_nop 0
	v_mul_f32_e32 v82, v82, v85
	v_exp_f32_e32 v85, v239
	s_nop 0
	v_add_f32_e32 v85, 1.0, v85
	v_rcp_f32_e32 v85, v85
	s_nop 0
	v_mul_f32_e32 v85, v231, v85
	v_exp_f32_e32 v90, v85
	s_nop 0
	v_fma_f32 v85, -v90, v90, 1.0
	v_sqrt_f32_e32 v85, v85
	s_nop 0
	v_mul_f32_e32 v91, v83, v85
	s_nop 1
	v_fmac_f32_dpp v80, v80, v84 row_shr:1 row_mask:0xf bank_mask:0xf
	v_fmac_f32_dpp v81, v81, v88 row_shr:1 row_mask:0xf bank_mask:0xf
	v_fmac_f32_dpp v82, v82, v89 row_shr:1 row_mask:0xf bank_mask:0xf
	v_fmac_f32_dpp v91, v91, v90 row_shr:1 row_mask:0xf bank_mask:0xf
	v_mul_f32_dpp v84, v84, v84 row_shr:1 row_mask:0xf bank_mask:0xf
	v_mul_f32_dpp v88, v88, v88 row_shr:1 row_mask:0xf bank_mask:0xf
	v_mul_f32_dpp v89, v89, v89 row_shr:1 row_mask:0xf bank_mask:0xf
	v_mul_f32_dpp v90, v90, v90 row_shr:1 row_mask:0xf bank_mask:0xf
	v_fmac_f32_dpp v80, v80, v84 row_shr:2 row_mask:0xf bank_mask:0xf
	v_fmac_f32_dpp v81, v81, v88 row_shr:2 row_mask:0xf bank_mask:0xf
	v_fmac_f32_dpp v82, v82, v89 row_shr:2 row_mask:0xf bank_mask:0xf
	v_fmac_f32_dpp v91, v91, v90 row_shr:2 row_mask:0xf bank_mask:0xf
	v_mul_f32_dpp v84, v84, v84 row_shr:2 row_mask:0xf bank_mask:0xf
; #define LAS __attribute__((address_space(3)))
; template <int PASS> __device__ __forceinline__ void phase_lru(LAS unsigned char* lds, const bf16_t* Z, const bf16_t* WL, float* LSUM, const float* LCAR, bf16_t* RNN,
;                                                               int S, int tid, int lane, int wave, int G) {
;     ...
;                 if (PASS == 0 && c == 0) {
; #pragma unroll
;                     for (int j = 0; j < 4; ++j) { float* sp = LSUM + ((size_t)(seg * 2 + 0) * LW + ch0 + j) * 2; sp[0] = Ac[j]; sp[1] = Hc[j]; }
;                 }
;             }
;             {
;                 f32x4 Hc = (f32x4){0.f, 0.f, 0.f, 0.f}, Ac = (f32x4){1.f, 1.f, 1.f, 1.f};
;                 if (PASS == 1) Hc = car[1];
; #pragma unroll
;                 for (int tt = 0; tt < 4; ++tt) { const int t = 3 - tt;
;                     f32x4 gr = (f32x4){0.f, 0.f, 0.f, 0.f}, gi = gr;
; #pragma unroll
;                     for (int s = 0; s < 4; ++s) { const bf16x8 bfr = *(const LAS bf16x8*)(lds + LRU_XC + off_b(16 * t + c, 4 * s + g4));
;                         gr = __builtin_amdgcn_mfma_f32_16x16x32_bf16(wf[2][s], bfr, gr, 0, 0, 0); gi = __builtin_amdgcn_mfma_f32_16x16x32_bf16(wf[3][s], bfr, gi, 0, 0, 0); }
;                     f32x4 ov;
;                     const f32x4 kba = kc[3 * 64 + lane], kbx = kc[4 * 64 + lane], ksp = kc[5 * 64 + lane];
;                     f32x4 av, hv;
; #pragma unroll
;                     for (int j = 0; j < 4; ++j) {
;                         const float rg = __builtin_amdgcn_rcpf(1.0f + __builtin_amdgcn_exp2f(fmaf(gr[j], -LOG2E, kba[j])));
;                         const float ig = __builtin_amdgcn_rcpf(1.0f + __builtin_amdgcn_exp2f(fmaf(gi[j], -LOG2E, kbx[j])));
;                         const float a_ = __builtin_amdgcn_exp2f(rg * ksp[j]);
;                         av[j] = a_; hv[j] = __builtin_amdgcn_sqrtf(fmaf(-a_, a_, 1.0f)) * (ig * xc[t][j]);
;                     }
	v_mul_f32_dpp v88, v88, v88 row_shr:2 row_mask:0xf bank_mask:0xf
	v_mul_f32_dpp v89, v89, v89 row_shr:2 row_mask:0xf bank_mask:0xf
	v_mul_f32_dpp v90, v90, v90 row_shr:2 row_mask:0xf bank_mask:0xf
	v_fmac_f32_dpp v80, v80, v84 row_shr:4 row_mask:0xf bank_mask:0xf
	v_fmac_f32_dpp v81, v81, v88 row_shr:4 row_mask:0xf bank_mask:0xf
	v_fmac_f32_dpp v82, v82, v89 row_shr:4 row_mask:0xf bank_mask:0xf
	v_fmac_f32_dpp v91, v91, v90 row_shr:4 row_mask:0xf bank_mask:0xf
	v_mul_f32_dpp v84, v84, v84 row_shr:4 row_mask:0xf bank_mask:0xf
	v_mul_f32_dpp v88, v88, v88 row_shr:4 row_mask:0xf bank_mask:0xf
	v_mul_f32_dpp v89, v89, v89 row_shr:4 row_mask:0xf bank_mask:0xf
	v_mul_f32_dpp v90, v90, v90 row_shr:4 row_mask:0xf bank_mask:0xf
	v_fmac_f32_dpp v80, v80, v84 row_shr:8 row_mask:0xf bank_mask:0xf
	v_fmac_f32_dpp v81, v81, v88 row_shr:8 row_mask:0xf bank_mask:0xf
	v_fmac_f32_dpp v82, v82, v89 row_shr:8 row_mask:0xf bank_mask:0xf
	v_fmac_f32_dpp v91, v91, v90 row_shr:8 row_mask:0xf bank_mask:0xf
	v_mul_f32_dpp v84, v84, v84 row_shr:8 row_mask:0xf bank_mask:0xf
	v_mul_f32_dpp v88, v88, v88 row_shr:8 row_mask:0xf bank_mask:0xf
	v_mul_f32_dpp v89, v89, v89 row_shr:8 row_mask:0xf bank_mask:0xf
	v_mul_f32_dpp v90, v90, v90 row_shr:8 row_mask:0xf bank_mask:0xf
	s_nop 1
	v_mov_b32_dpp v86, v84 row_newbcast:15 row_mask:0xf bank_mask:0xf
	v_fmac_f32_e32 v80, v84, v145
	v_fmac_f32_e32 v81, v88, v146
	v_fmac_f32_e32 v82, v89, v147
	v_fmac_f32_e32 v91, v90, v184
	v_mov_b32_dpp v87, v80 row_newbcast:15 row_mask:0xf bank_mask:0xf
	v_mov_b32_dpp v85, v81 row_newbcast:15 row_mask:0xf bank_mask:0xf
	v_mov_b32_dpp v84, v88 row_newbcast:15 row_mask:0xf bank_mask:0xf
	v_mov_b32_dpp v83, v82 row_newbcast:15 row_mask:0xf bank_mask:0xf
	v_mov_b32_dpp v82, v89 row_newbcast:15 row_mask:0xf bank_mask:0xf
	v_mov_b32_dpp v81, v91 row_newbcast:15 row_mask:0xf bank_mask:0xf
	v_mov_b32_dpp v80, v90 row_newbcast:15 row_mask:0xf bank_mask:0xf
	v_lshl_add_u64 v[146:147], v[2:3], 0, s[0:1]
	v_lshl_add_u64 v[144:145], v[106:107], 0, s[0:1]
	s_and_saveexec_b64 s[18:19], s[40:41]
	s_cbranch_execz .LBB0_235
	v_mul_f32_e32 v88, v175, v179
	v_mul_f32_e32 v88, v88, v183
	s_waitcnt lgkmcnt(0)
	v_mul_f32_e32 v80, v88, v80
	v_mul_f32_e32 v88, v174, v178
	v_mul_f32_e32 v88, v88, v182
	v_mul_f32_e32 v82, v88, v82
	v_mul_f32_e32 v88, v173, v177
	v_mul_f32_e32 v88, v88, v181
	v_mul_f32_e32 v1, v1, v176
	v_mul_f32_e32 v84, v88, v84
	v_mul_f32_e32 v1, v1, v180
	v_add_co_u32_e32 v88, vcc, 0x8300000, v144
	v_mul_f32_e32 v86, v1, v86
	s_nop 0
	v_addc_co_u32_e32 v89, vcc, 0, v145, vcc
	global_store_dwordx2 v[88:89], v[86:87], off
	v_or_b32_e32 v86, 8, v146
	v_mov_b32_e32 v87, v147
	v_lshl_add_u64 v[86:87], s[10:11], 0, v[86:87]
	global_store_dwordx2 v[86:87], v[84:85], off
	v_or_b32_e32 v84, 16, v146
	v_mov_b32_e32 v85, v147
	v_lshl_add_u64 v[84:85], s[10:11], 0, v[84:85]
	global_store_dwordx2 v[84:85], v[82:83], off
	v_or_b32_e32 v82, 24, v146
	v_mov_b32_e32 v83, v147
	v_lshl_add_u64 v[82:83], s[10:11], 0, v[82:83]
	global_store_dwordx2 v[82:83], v[80:81], off
.LBB0_235:
	s_or_b64 exec, exec, s[18:19]
	s_waitcnt lgkmcnt(0)
	ds_read_b128 v[220:223], v155 offset:39936
	ds_read_b128 v[224:227], v155 offset:40960
	ds_read_b128 v[228:231], v155 offset:41984
	ds_read_b128 v[204:207], v169 offset:30720
	ds_read_b128 v[208:211], v170 offset:30720
	ds_read_b128 v[212:215], v172 offset:30720
	ds_read_b128 v[216:219], v171 offset:30720
	s_waitcnt lgkmcnt(0)
	v_mfma_f32_16x16x32_bf16 v[236:239], v[36:39], v[204:207], v[220:223]
	v_mfma_f32_16x16x32_bf16 v[240:243], v[52:55], v[204:207], v[224:227]
	v_mfma_f32_16x16x32_bf16 v[236:239], v[40:43], v[208:211], v[236:239]
	v_mfma_f32_16x16x32_bf16 v[240:243], v[56:59], v[208:211], v[240:243]
	v_mfma_f32_16x16x32_bf16 v[236:239], v[44:47], v[216:219], v[236:239]
	v_mfma_f32_16x16x32_bf16 v[240:243], v[60:63], v[216:219], v[240:243]
	v_mfma_f32_16x16x32_bf16 v[236:239], v[48:51], v[212:215], v[236:239]
	v_mfma_f32_16x16x32_bf16 v[240:243], v[64:67], v[212:215], v[240:243]
	s_nop 7
	s_nop 1
	v_exp_f32_e32 v1, v236
	v_exp_f32_e32 v80, v240
	v_add_f32_e32 v1, 1.0, v1
	v_rcp_f32_e32 v1, v1
	v_add_f32_e32 v80, 1.0, v80
	v_rcp_f32_e32 v80, v80
	v_exp_f32_e32 v81, v241
	v_mul_f32_e32 v1, v228, v1
	v_exp_f32_e32 v1, v1
	v_mul_f32_e32 v80, v128, v80
	v_add_f32_e32 v81, 1.0, v81
	v_rcp_f32_e32 v81, v81
	v_fma_f32 v84, -v1, v1, 1.0
	v_sqrt_f32_e32 v84, v84
	v_mul_f32_e32 v81, v129, v81
	v_exp_f32_e32 v82, v242
	v_mul_f32_e32 v80, v80, v84
	v_exp_f32_e32 v84, v237
	v_add_f32_e32 v82, 1.0, v82
	v_rcp_f32_e32 v82, v82
	v_add_f32_e32 v84, 1.0, v84
	v_rcp_f32_e32 v84, v84
	v_mul_f32_e32 v82, v126, v82
	v_exp_f32_e32 v83, v243
	ds_read_b128 v[204:207], v169 offset:26624
	ds_read_b128 v[208:211], v170 offset:26624
	ds_read_b128 v[212:215], v172 offset:26624
	ds_read_b128 v[216:219], v171 offset:26624
	v_mul_f32_e32 v84, v229, v84
	v_exp_f32_e32 v84, v84
	v_add_f32_e32 v83, 1.0, v83
	v_rcp_f32_e32 v83, v83
	v_fma_f32 v85, -v84, v84, 1.0
	v_sqrt_f32_e32 v85, v85
	v_mul_f32_e32 v83, v127, v83
	v_mul_f32_e32 v81, v81, v85
	v_exp_f32_e32 v85, v238
	s_nop 0
	v_add_f32_e32 v85, 1.0, v85
	v_rcp_f32_e32 v85, v85
	s_nop 0
	v_mul_f32_e32 v85, v230, v85
	v_exp_f32_e32 v85, v85
	s_nop 0
	v_fma_f32 v86, -v85, v85, 1.0
	v_sqrt_f32_e32 v86, v86
	s_nop 0
	v_mul_f32_e32 v82, v82, v86
	v_exp_f32_e32 v86, v239
	s_nop 0
	v_add_f32_e32 v86, 1.0, v86
	v_rcp_f32_e32 v86, v86
	s_nop 0
	v_mul_f32_e32 v86, v231, v86
	v_exp_f32_e32 v86, v86
	s_nop 0
	v_fma_f32 v87, -v86, v86, 1.0
	v_sqrt_f32_e32 v87, v87
	s_nop 0
	v_mul_f32_e32 v83, v83, v87
	s_waitcnt lgkmcnt(0)
; template <int PASS> __device__ __forceinline__ void phase_lru(LAS unsigned char* lds, const bf16_t* Z, const bf16_t* WL, float* LSUM, const float* LCAR, bf16_t* RNN,
;                                                               int S, int tid, int lane, int wave, int G) {
;     ...
;                 for (int tt = 0; tt < 4; ++tt) { const int t = 3 - tt;
;                     f32x4 gr = (f32x4){0.f, 0.f, 0.f, 0.f}, gi = gr;
; #pragma unroll
;                     for (int s = 0; s < 4; ++s) { const bf16x8 bfr = *(const LAS bf16x8*)(lds + LRU_XC + off_b(16 * t + c, 4 * s + g4));
;                         gr = __builtin_amdgcn_mfma_f32_16x16x32_bf16(wf[2][s], bfr, gr, 0, 0, 0); gi = __builtin_amdgcn_mfma_f32_16x16x32_bf16(wf[3][s], bfr, gi, 0, 0, 0); }
;                     f32x4 ov;
;                     const f32x4 kba = kc[3 * 64 + lane], kbx = kc[4 * 64 + lane], ksp = kc[5 * 64 + lane];
;                     f32x4 av, hv;
; #pragma unroll
;                     for (int j = 0; j < 4; ++j) {
;                         const float rg = __builtin_amdgcn_rcpf(1.0f + __builtin_amdgcn_exp2f(fmaf(gr[j], -LOG2E, kba[j])));
;                         const float ig = __builtin_amdgcn_rcpf(1.0f + __builtin_amdgcn_exp2f(fmaf(gi[j], -LOG2E, kbx[j])));
;                         const float a_ = __builtin_amdgcn_exp2f(rg * ksp[j]);
;                         av[j] = a_; hv[j] = __builtin_amdgcn_sqrtf(fmaf(-a_, a_, 1.0f)) * (ig * xc[t][j]);
;                     }
;                     lru_scan4_bwd(av, hv);
; #pragma unroll
;                     for (int j = 0; j < 4; ++j) {
;                         const float hfull = fmaf(av[j], Hc[j], hv[j]);
;                         Hc[j] = __shfl(hfull, lane & 48);
;                         if (PASS == 0) Ac[j] *= __shfl(av[j], lane & 48);
;                         if (PASS == 1) { const unsigned rw = j < 2 ? ryr[t].x : ryr[t].y; const float y = (j & 1) ? bfhi(rw) : bflo(rw);
;                             const float ge = y * __builtin_amdgcn_rcpf(1.0f + __builtin_amdgcn_exp2f((-2.3022082f * y) * fmaf(0.044715f * y, y, 1.0f)));
;                             ov[j] = (hf[t][j] + hfull) * ge; }
;                     }
;                     if (PASS == 1) { u32x2 w; w.x = pk2(ov[0], ov[1]); w.y = pk2(ov[2], ov[3]); *(u32x2*)(RNN + (size_t)(t0 + 16 * t + c) * LW + ch0) = w; }
;                     __builtin_amdgcn_sched_barrier(0);
	v_mfma_f32_16x16x32_bf16 v[236:239], v[36:39], v[204:207], v[220:223]
	v_mfma_f32_16x16x32_bf16 v[240:243], v[52:55], v[204:207], v[224:227]
	v_mfma_f32_16x16x32_bf16 v[236:239], v[40:43], v[208:211], v[236:239]
	v_mfma_f32_16x16x32_bf16 v[240:243], v[56:59], v[208:211], v[240:243]
	v_mfma_f32_16x16x32_bf16 v[236:239], v[44:47], v[216:219], v[236:239]
	v_mfma_f32_16x16x32_bf16 v[240:243], v[60:63], v[216:219], v[240:243]
	v_mfma_f32_16x16x32_bf16 v[236:239], v[48:51], v[212:215], v[236:239]
	v_mfma_f32_16x16x32_bf16 v[240:243], v[64:67], v[212:215], v[240:243]
	s_nop 1
	v_fmac_f32_dpp v80, v80, v1 row_shl:1 row_mask:0xf bank_mask:0xf
	v_fmac_f32_dpp v81, v81, v84 row_shl:1 row_mask:0xf bank_mask:0xf
	v_fmac_f32_dpp v82, v82, v85 row_shl:1 row_mask:0xf bank_mask:0xf
	v_fmac_f32_dpp v83, v83, v86 row_shl:1 row_mask:0xf bank_mask:0xf
	v_mul_f32_dpp v1, v1, v1 row_shl:1 row_mask:0xf bank_mask:0xf
	v_mul_f32_dpp v84, v84, v84 row_shl:1 row_mask:0xf bank_mask:0xf
	v_mul_f32_dpp v85, v85, v85 row_shl:1 row_mask:0xf bank_mask:0xf
	v_mul_f32_dpp v86, v86, v86 row_shl:1 row_mask:0xf bank_mask:0xf
	v_fmac_f32_dpp v80, v80, v1 row_shl:2 row_mask:0xf bank_mask:0xf
	v_fmac_f32_dpp v81, v81, v84 row_shl:2 row_mask:0xf bank_mask:0xf
	v_fmac_f32_dpp v82, v82, v85 row_shl:2 row_mask:0xf bank_mask:0xf
	v_fmac_f32_dpp v83, v83, v86 row_shl:2 row_mask:0xf bank_mask:0xf
	v_mul_f32_dpp v1, v1, v1 row_shl:2 row_mask:0xf bank_mask:0xf
	v_mul_f32_dpp v84, v84, v84 row_shl:2 row_mask:0xf bank_mask:0xf
	v_mul_f32_dpp v85, v85, v85 row_shl:2 row_mask:0xf bank_mask:0xf
	v_mul_f32_dpp v86, v86, v86 row_shl:2 row_mask:0xf bank_mask:0xf
	v_fmac_f32_dpp v80, v80, v1 row_shl:4 row_mask:0xf bank_mask:0xf
	v_fmac_f32_dpp v81, v81, v84 row_shl:4 row_mask:0xf bank_mask:0xf
	v_fmac_f32_dpp v82, v82, v85 row_shl:4 row_mask:0xf bank_mask:0xf
	v_fmac_f32_dpp v83, v83, v86 row_shl:4 row_mask:0xf bank_mask:0xf
	v_mul_f32_dpp v1, v1, v1 row_shl:4 row_mask:0xf bank_mask:0xf
	v_mul_f32_dpp v84, v84, v84 row_shl:4 row_mask:0xf bank_mask:0xf
	v_mul_f32_dpp v85, v85, v85 row_shl:4 row_mask:0xf bank_mask:0xf
	v_mul_f32_dpp v86, v86, v86 row_shl:4 row_mask:0xf bank_mask:0xf
	v_fmac_f32_dpp v80, v80, v1 row_shl:8 row_mask:0xf bank_mask:0xf
	v_fmac_f32_dpp v81, v81, v84 row_shl:8 row_mask:0xf bank_mask:0xf
	v_fmac_f32_dpp v82, v82, v85 row_shl:8 row_mask:0xf bank_mask:0xf
	v_fmac_f32_dpp v83, v83, v86 row_shl:8 row_mask:0xf bank_mask:0xf
	v_mul_f32_dpp v1, v1, v1 row_shl:8 row_mask:0xf bank_mask:0xf
	v_mul_f32_dpp v84, v84, v84 row_shl:8 row_mask:0xf bank_mask:0xf
	v_mul_f32_dpp v85, v85, v85 row_shl:8 row_mask:0xf bank_mask:0xf
	v_mul_f32_dpp v86, v86, v86 row_shl:8 row_mask:0xf bank_mask:0xf
	s_nop 1
	v_mov_b32_dpp v126, v84 row_newbcast:0 row_mask:0xf bank_mask:0xf
	v_fmac_f32_e32 v80, 0, v1
	v_mov_b32_dpp v1, v1 row_newbcast:0 row_mask:0xf bank_mask:0xf
	v_mov_b32_dpp v127, v85 row_newbcast:0 row_mask:0xf bank_mask:0xf
	v_mov_b32_dpp v128, v86 row_newbcast:0 row_mask:0xf bank_mask:0xf
	v_fmac_f32_e32 v81, 0, v84
	v_fmac_f32_e32 v82, 0, v85
	v_fmac_f32_e32 v83, 0, v86
	v_mov_b32_dpp v129, v80 row_newbcast:0 row_mask:0xf bank_mask:0xf
	v_mov_b32_dpp v173, v81 row_newbcast:0 row_mask:0xf bank_mask:0xf
	v_mov_b32_dpp v174, v82 row_newbcast:0 row_mask:0xf bank_mask:0xf
	v_mov_b32_dpp v175, v83 row_newbcast:0 row_mask:0xf bank_mask:0xf
	v_exp_f32_e32 v88, v236
	v_exp_f32_e32 v80, v240
	v_add_f32_e32 v88, 1.0, v88
	v_rcp_f32_e32 v88, v88
	v_add_f32_e32 v80, 1.0, v80
	v_rcp_f32_e32 v80, v80
	v_exp_f32_e32 v81, v241
	v_mul_f32_e32 v84, v228, v88
	v_exp_f32_e32 v84, v84
	v_mul_f32_e32 v80, v124, v80
	v_add_f32_e32 v81, 1.0, v81
	v_rcp_f32_e32 v81, v81
	v_fma_f32 v88, -v84, v84, 1.0
	v_sqrt_f32_e32 v88, v88
	v_mul_f32_e32 v81, v125, v81
	v_exp_f32_e32 v82, v242
	v_mul_f32_e32 v80, v80, v88
	v_exp_f32_e32 v88, v237
	v_add_f32_e32 v82, 1.0, v82
	v_rcp_f32_e32 v82, v82
	v_add_f32_e32 v88, 1.0, v88
	v_rcp_f32_e32 v88, v88
	v_mul_f32_e32 v82, v122, v82
	v_exp_f32_e32 v83, v243
	ds_read_b128 v[204:207], v169 offset:22528
	ds_read_b128 v[208:211], v170 offset:22528
	ds_read_b128 v[212:215], v172 offset:22528
	ds_read_b128 v[216:219], v171 offset:22528
	v_mul_f32_e32 v85, v229, v88
	v_exp_f32_e32 v85, v85
	v_add_f32_e32 v83, 1.0, v83
	v_rcp_f32_e32 v83, v83
	v_fma_f32 v88, -v85, v85, 1.0
	v_sqrt_f32_e32 v88, v88
	v_mul_f32_e32 v83, v123, v83
	v_mul_f32_e32 v81, v81, v88
	v_exp_f32_e32 v88, v238
	s_nop 0
	v_add_f32_e32 v88, 1.0, v88
	v_rcp_f32_e32 v88, v88
	s_nop 0
	v_mul_f32_e32 v86, v230, v88
	v_exp_f32_e32 v86, v86
	s_nop 0
	v_fma_f32 v88, -v86, v86, 1.0
	v_sqrt_f32_e32 v88, v88
	s_nop 0
	v_mul_f32_e32 v82, v82, v88
	v_exp_f32_e32 v88, v239
	s_nop 0
	v_add_f32_e32 v88, 1.0, v88
	v_rcp_f32_e32 v88, v88
	s_nop 0
	v_mul_f32_e32 v87, v231, v88
	v_exp_f32_e32 v87, v87
	s_nop 0
	v_fma_f32 v88, -v87, v87, 1.0
	v_sqrt_f32_e32 v88, v88
	s_nop 0
	v_mul_f32_e32 v83, v83, v88
	s_waitcnt lgkmcnt(0)
; template <int PASS> __device__ __forceinline__ void phase_lru(LAS unsigned char* lds, const bf16_t* Z, const bf16_t* WL, float* LSUM, const float* LCAR, bf16_t* RNN,
;                                                               int S, int tid, int lane, int wave, int G) {
;     ...
;                 for (int tt = 0; tt < 4; ++tt) { const int t = 3 - tt;
;                     f32x4 gr = (f32x4){0.f, 0.f, 0.f, 0.f}, gi = gr;
; #pragma unroll
;                     for (int s = 0; s < 4; ++s) { const bf16x8 bfr = *(const LAS bf16x8*)(lds + LRU_XC + off_b(16 * t + c, 4 * s + g4));
;                         gr = __builtin_amdgcn_mfma_f32_16x16x32_bf16(wf[2][s], bfr, gr, 0, 0, 0); gi = __builtin_amdgcn_mfma_f32_16x16x32_bf16(wf[3][s], bfr, gi, 0, 0, 0); }
;                     f32x4 ov;
;                     const f32x4 kba = kc[3 * 64 + lane], kbx = kc[4 * 64 + lane], ksp = kc[5 * 64 + lane];
;                     f32x4 av, hv;
; #pragma unroll
;                     for (int j = 0; j < 4; ++j) {
;                         const float rg = __builtin_amdgcn_rcpf(1.0f + __builtin_amdgcn_exp2f(fmaf(gr[j], -LOG2E, kba[j])));
;                         const float ig = __builtin_amdgcn_rcpf(1.0f + __builtin_amdgcn_exp2f(fmaf(gi[j], -LOG2E, kbx[j])));
;                         const float a_ = __builtin_amdgcn_exp2f(rg * ksp[j]);
;                         av[j] = a_; hv[j] = __builtin_amdgcn_sqrtf(fmaf(-a_, a_, 1.0f)) * (ig * xc[t][j]);
;                     }
;                     lru_scan4_bwd(av, hv);
; #pragma unroll
;                     for (int j = 0; j < 4; ++j) {
;                         const float hfull = fmaf(av[j], Hc[j], hv[j]);
;                         Hc[j] = __shfl(hfull, lane & 48);
;                         if (PASS == 0) Ac[j] *= __shfl(av[j], lane & 48);
;                         if (PASS == 1) { const unsigned rw = j < 2 ? ryr[t].x : ryr[t].y; const float y = (j & 1) ? bfhi(rw) : bflo(rw);
;                             const float ge = y * __builtin_amdgcn_rcpf(1.0f + __builtin_amdgcn_exp2f((-2.3022082f * y) * fmaf(0.044715f * y, y, 1.0f)));
;                             ov[j] = (hf[t][j] + hfull) * ge; }
;                     }
;                     if (PASS == 1) { u32x2 w; w.x = pk2(ov[0], ov[1]); w.y = pk2(ov[2], ov[3]); *(u32x2*)(RNN + (size_t)(t0 + 16 * t + c) * LW + ch0) = w; }
;                     __builtin_amdgcn_sched_barrier(0);
	v_mfma_f32_16x16x32_bf16 v[236:239], v[36:39], v[204:207], v[220:223]
	v_mfma_f32_16x16x32_bf16 v[240:243], v[52:55], v[204:207], v[224:227]
	v_mfma_f32_16x16x32_bf16 v[236:239], v[40:43], v[208:211], v[236:239]
	v_mfma_f32_16x16x32_bf16 v[240:243], v[56:59], v[208:211], v[240:243]
	v_mfma_f32_16x16x32_bf16 v[236:239], v[44:47], v[216:219], v[236:239]
	v_mfma_f32_16x16x32_bf16 v[240:243], v[60:63], v[216:219], v[240:243]
	v_mfma_f32_16x16x32_bf16 v[236:239], v[48:51], v[212:215], v[236:239]
	v_mfma_f32_16x16x32_bf16 v[240:243], v[64:67], v[212:215], v[240:243]
	s_nop 1
	v_fmac_f32_dpp v80, v80, v84 row_shl:1 row_mask:0xf bank_mask:0xf
	v_fmac_f32_dpp v81, v81, v85 row_shl:1 row_mask:0xf bank_mask:0xf
	v_fmac_f32_dpp v82, v82, v86 row_shl:1 row_mask:0xf bank_mask:0xf
	v_fmac_f32_dpp v83, v83, v87 row_shl:1 row_mask:0xf bank_mask:0xf
	v_mul_f32_dpp v84, v84, v84 row_shl:1 row_mask:0xf bank_mask:0xf
	v_mul_f32_dpp v85, v85, v85 row_shl:1 row_mask:0xf bank_mask:0xf
	v_mul_f32_dpp v86, v86, v86 row_shl:1 row_mask:0xf bank_mask:0xf
	v_mul_f32_dpp v87, v87, v87 row_shl:1 row_mask:0xf bank_mask:0xf
	v_fmac_f32_dpp v80, v80, v84 row_shl:2 row_mask:0xf bank_mask:0xf
	v_fmac_f32_dpp v81, v81, v85 row_shl:2 row_mask:0xf bank_mask:0xf
	v_fmac_f32_dpp v82, v82, v86 row_shl:2 row_mask:0xf bank_mask:0xf
	v_fmac_f32_dpp v83, v83, v87 row_shl:2 row_mask:0xf bank_mask:0xf
	v_mul_f32_dpp v84, v84, v84 row_shl:2 row_mask:0xf bank_mask:0xf
	v_mul_f32_dpp v85, v85, v85 row_shl:2 row_mask:0xf bank_mask:0xf
	v_mul_f32_dpp v86, v86, v86 row_shl:2 row_mask:0xf bank_mask:0xf
	v_mul_f32_dpp v87, v87, v87 row_shl:2 row_mask:0xf bank_mask:0xf
	v_fmac_f32_dpp v80, v80, v84 row_shl:4 row_mask:0xf bank_mask:0xf
	v_fmac_f32_dpp v81, v81, v85 row_shl:4 row_mask:0xf bank_mask:0xf
	v_fmac_f32_dpp v82, v82, v86 row_shl:4 row_mask:0xf bank_mask:0xf
	v_fmac_f32_dpp v83, v83, v87 row_shl:4 row_mask:0xf bank_mask:0xf
	v_mul_f32_dpp v84, v84, v84 row_shl:4 row_mask:0xf bank_mask:0xf
	v_mul_f32_dpp v85, v85, v85 row_shl:4 row_mask:0xf bank_mask:0xf
	v_mul_f32_dpp v86, v86, v86 row_shl:4 row_mask:0xf bank_mask:0xf
	v_mul_f32_dpp v87, v87, v87 row_shl:4 row_mask:0xf bank_mask:0xf
	v_fmac_f32_dpp v80, v80, v84 row_shl:8 row_mask:0xf bank_mask:0xf
	v_fmac_f32_dpp v81, v81, v85 row_shl:8 row_mask:0xf bank_mask:0xf
	v_fmac_f32_dpp v82, v82, v86 row_shl:8 row_mask:0xf bank_mask:0xf
	v_fmac_f32_dpp v83, v83, v87 row_shl:8 row_mask:0xf bank_mask:0xf
	v_mul_f32_dpp v84, v84, v84 row_shl:8 row_mask:0xf bank_mask:0xf
	v_mul_f32_dpp v85, v85, v85 row_shl:8 row_mask:0xf bank_mask:0xf
	v_mul_f32_dpp v86, v86, v86 row_shl:8 row_mask:0xf bank_mask:0xf
	v_mul_f32_dpp v87, v87, v87 row_shl:8 row_mask:0xf bank_mask:0xf
	s_nop 1
	v_mov_b32_dpp v122, v84 row_newbcast:0 row_mask:0xf bank_mask:0xf
	v_mov_b32_dpp v123, v85 row_newbcast:0 row_mask:0xf bank_mask:0xf
	v_mov_b32_dpp v124, v86 row_newbcast:0 row_mask:0xf bank_mask:0xf
	v_mov_b32_dpp v125, v87 row_newbcast:0 row_mask:0xf bank_mask:0xf
	v_fmac_f32_e32 v80, v84, v129
	v_fmac_f32_e32 v81, v85, v173
	v_fmac_f32_e32 v82, v86, v174
	v_fmac_f32_e32 v83, v87, v175
	v_mov_b32_dpp v129, v80 row_newbcast:0 row_mask:0xf bank_mask:0xf
	v_mov_b32_dpp v173, v81 row_newbcast:0 row_mask:0xf bank_mask:0xf
	v_mov_b32_dpp v174, v82 row_newbcast:0 row_mask:0xf bank_mask:0xf
	v_mov_b32_dpp v175, v83 row_newbcast:0 row_mask:0xf bank_mask:0xf
	v_exp_f32_e32 v88, v236
	v_exp_f32_e32 v80, v240
	v_add_f32_e32 v88, 1.0, v88
	v_rcp_f32_e32 v88, v88
	v_add_f32_e32 v80, 1.0, v80
	v_rcp_f32_e32 v80, v80
	v_exp_f32_e32 v81, v241
	v_mul_f32_e32 v84, v228, v88
	v_exp_f32_e32 v84, v84
	v_mul_f32_e32 v80, v120, v80
	v_add_f32_e32 v81, 1.0, v81
	v_rcp_f32_e32 v81, v81
	v_fma_f32 v88, -v84, v84, 1.0
	v_sqrt_f32_e32 v88, v88
	v_mul_f32_e32 v81, v121, v81
	v_exp_f32_e32 v82, v242
	v_mul_f32_e32 v80, v80, v88
	v_exp_f32_e32 v88, v237
	v_add_f32_e32 v82, 1.0, v82
	v_rcp_f32_e32 v82, v82
	v_add_f32_e32 v88, 1.0, v88
	v_rcp_f32_e32 v88, v88
	v_mul_f32_e32 v82, v118, v82
	v_exp_f32_e32 v83, v243
	ds_read_b128 v[204:207], v169 offset:18432
	ds_read_b128 v[208:211], v170 offset:18432
	ds_read_b128 v[212:215], v172 offset:18432
	ds_read_b128 v[216:219], v171 offset:18432
	v_mul_f32_e32 v85, v229, v88
	v_exp_f32_e32 v85, v85
	v_add_f32_e32 v83, 1.0, v83
	v_rcp_f32_e32 v83, v83
	v_fma_f32 v88, -v85, v85, 1.0
	v_sqrt_f32_e32 v88, v88
	v_mul_f32_e32 v83, v119, v83
	v_mul_f32_e32 v81, v81, v88
	v_exp_f32_e32 v88, v238
	s_nop 0
	v_add_f32_e32 v88, 1.0, v88
	v_rcp_f32_e32 v88, v88
	s_nop 0
	v_mul_f32_e32 v86, v230, v88
	v_exp_f32_e32 v86, v86
	s_nop 0
	v_fma_f32 v88, -v86, v86, 1.0
	v_sqrt_f32_e32 v88, v88
	s_nop 0
	v_mul_f32_e32 v82, v82, v88
	v_exp_f32_e32 v88, v239
	s_nop 0
	v_add_f32_e32 v88, 1.0, v88
	v_rcp_f32_e32 v88, v88
	s_nop 0
	v_mul_f32_e32 v87, v231, v88
	v_exp_f32_e32 v87, v87
	s_nop 0
	v_fma_f32 v88, -v87, v87, 1.0
	v_sqrt_f32_e32 v88, v88
	s_nop 0
	v_mul_f32_e32 v83, v83, v88
	s_waitcnt lgkmcnt(0)
; template <int PASS> __device__ __forceinline__ void phase_lru(LAS unsigned char* lds, const bf16_t* Z, const bf16_t* WL, float* LSUM, const float* LCAR, bf16_t* RNN,
;                                                               int S, int tid, int lane, int wave, int G) {
;     ...
;                 for (int tt = 0; tt < 4; ++tt) { const int t = 3 - tt;
;                     f32x4 gr = (f32x4){0.f, 0.f, 0.f, 0.f}, gi = gr;
; #pragma unroll
;                     for (int s = 0; s < 4; ++s) { const bf16x8 bfr = *(const LAS bf16x8*)(lds + LRU_XC + off_b(16 * t + c, 4 * s + g4));
;                         gr = __builtin_amdgcn_mfma_f32_16x16x32_bf16(wf[2][s], bfr, gr, 0, 0, 0); gi = __builtin_amdgcn_mfma_f32_16x16x32_bf16(wf[3][s], bfr, gi, 0, 0, 0); }
;                     f32x4 ov;
;                     const f32x4 kba = kc[3 * 64 + lane], kbx = kc[4 * 64 + lane], ksp = kc[5 * 64 + lane];
;                     f32x4 av, hv;
; #pragma unroll
;                     for (int j = 0; j < 4; ++j) {
;                         const float rg = __builtin_amdgcn_rcpf(1.0f + __builtin_amdgcn_exp2f(fmaf(gr[j], -LOG2E, kba[j])));
;                         const float ig = __builtin_amdgcn_rcpf(1.0f + __builtin_amdgcn_exp2f(fmaf(gi[j], -LOG2E, kbx[j])));
;                         const float a_ = __builtin_amdgcn_exp2f(rg * ksp[j]);
;                         av[j] = a_; hv[j] = __builtin_amdgcn_sqrtf(fmaf(-a_, a_, 1.0f)) * (ig * xc[t][j]);
;                     }
;                     lru_scan4_bwd(av, hv);
; #pragma unroll
;                     for (int j = 0; j < 4; ++j) {
;                         const float hfull = fmaf(av[j], Hc[j], hv[j]);
;                         Hc[j] = __shfl(hfull, lane & 48);
;                         if (PASS == 0) Ac[j] *= __shfl(av[j], lane & 48);
;                         if (PASS == 1) { const unsigned rw = j < 2 ? ryr[t].x : ryr[t].y; const float y = (j & 1) ? bfhi(rw) : bflo(rw);
;                             const float ge = y * __builtin_amdgcn_rcpf(1.0f + __builtin_amdgcn_exp2f((-2.3022082f * y) * fmaf(0.044715f * y, y, 1.0f)));
;                             ov[j] = (hf[t][j] + hfull) * ge; }
;                     }
;                     if (PASS == 1) { u32x2 w; w.x = pk2(ov[0], ov[1]); w.y = pk2(ov[2], ov[3]); *(u32x2*)(RNN + (size_t)(t0 + 16 * t + c) * LW + ch0) = w; }
;                     __builtin_amdgcn_sched_barrier(0);
	v_mfma_f32_16x16x32_bf16 v[236:239], v[36:39], v[204:207], v[220:223]
	v_mfma_f32_16x16x32_bf16 v[240:243], v[52:55], v[204:207], v[224:227]
	v_mfma_f32_16x16x32_bf16 v[236:239], v[40:43], v[208:211], v[236:239]
	v_mfma_f32_16x16x32_bf16 v[240:243], v[56:59], v[208:211], v[240:243]
	v_mfma_f32_16x16x32_bf16 v[236:239], v[44:47], v[216:219], v[236:239]
	v_mfma_f32_16x16x32_bf16 v[240:243], v[60:63], v[216:219], v[240:243]
	v_mfma_f32_16x16x32_bf16 v[236:239], v[48:51], v[212:215], v[236:239]
	v_mfma_f32_16x16x32_bf16 v[240:243], v[64:67], v[212:215], v[240:243]
	s_nop 1
	v_fmac_f32_dpp v80, v80, v84 row_shl:1 row_mask:0xf bank_mask:0xf
	v_fmac_f32_dpp v81, v81, v85 row_shl:1 row_mask:0xf bank_mask:0xf
	v_fmac_f32_dpp v82, v82, v86 row_shl:1 row_mask:0xf bank_mask:0xf
	v_fmac_f32_dpp v83, v83, v87 row_shl:1 row_mask:0xf bank_mask:0xf
	v_mul_f32_dpp v84, v84, v84 row_shl:1 row_mask:0xf bank_mask:0xf
	v_mul_f32_dpp v85, v85, v85 row_shl:1 row_mask:0xf bank_mask:0xf
	v_mul_f32_dpp v86, v86, v86 row_shl:1 row_mask:0xf bank_mask:0xf
	v_mul_f32_dpp v87, v87, v87 row_shl:1 row_mask:0xf bank_mask:0xf
	v_fmac_f32_dpp v80, v80, v84 row_shl:2 row_mask:0xf bank_mask:0xf
	v_fmac_f32_dpp v81, v81, v85 row_shl:2 row_mask:0xf bank_mask:0xf
	v_fmac_f32_dpp v82, v82, v86 row_shl:2 row_mask:0xf bank_mask:0xf
	v_fmac_f32_dpp v83, v83, v87 row_shl:2 row_mask:0xf bank_mask:0xf
	v_mul_f32_dpp v84, v84, v84 row_shl:2 row_mask:0xf bank_mask:0xf
	v_mul_f32_dpp v85, v85, v85 row_shl:2 row_mask:0xf bank_mask:0xf
	v_mul_f32_dpp v86, v86, v86 row_shl:2 row_mask:0xf bank_mask:0xf
	v_mul_f32_dpp v87, v87, v87 row_shl:2 row_mask:0xf bank_mask:0xf
	v_fmac_f32_dpp v80, v80, v84 row_shl:4 row_mask:0xf bank_mask:0xf
	v_fmac_f32_dpp v81, v81, v85 row_shl:4 row_mask:0xf bank_mask:0xf
	v_fmac_f32_dpp v82, v82, v86 row_shl:4 row_mask:0xf bank_mask:0xf
	v_fmac_f32_dpp v83, v83, v87 row_shl:4 row_mask:0xf bank_mask:0xf
	v_mul_f32_dpp v84, v84, v84 row_shl:4 row_mask:0xf bank_mask:0xf
	v_mul_f32_dpp v85, v85, v85 row_shl:4 row_mask:0xf bank_mask:0xf
	v_mul_f32_dpp v86, v86, v86 row_shl:4 row_mask:0xf bank_mask:0xf
	v_mul_f32_dpp v87, v87, v87 row_shl:4 row_mask:0xf bank_mask:0xf
	v_fmac_f32_dpp v80, v80, v84 row_shl:8 row_mask:0xf bank_mask:0xf
	v_fmac_f32_dpp v81, v81, v85 row_shl:8 row_mask:0xf bank_mask:0xf
	v_fmac_f32_dpp v82, v82, v86 row_shl:8 row_mask:0xf bank_mask:0xf
	v_fmac_f32_dpp v83, v83, v87 row_shl:8 row_mask:0xf bank_mask:0xf
	v_mul_f32_dpp v84, v84, v84 row_shl:8 row_mask:0xf bank_mask:0xf
	v_mul_f32_dpp v85, v85, v85 row_shl:8 row_mask:0xf bank_mask:0xf
	v_mul_f32_dpp v86, v86, v86 row_shl:8 row_mask:0xf bank_mask:0xf
	v_mul_f32_dpp v87, v87, v87 row_shl:8 row_mask:0xf bank_mask:0xf
	s_nop 1
	v_mov_b32_dpp v118, v84 row_newbcast:0 row_mask:0xf bank_mask:0xf
	v_mov_b32_dpp v119, v85 row_newbcast:0 row_mask:0xf bank_mask:0xf
	v_mov_b32_dpp v120, v86 row_newbcast:0 row_mask:0xf bank_mask:0xf
	v_mov_b32_dpp v121, v87 row_newbcast:0 row_mask:0xf bank_mask:0xf
	v_fmac_f32_e32 v80, v84, v129
	v_fmac_f32_e32 v81, v85, v173
	v_fmac_f32_e32 v82, v86, v174
	v_fmac_f32_e32 v83, v87, v175
	v_mov_b32_dpp v129, v80 row_newbcast:0 row_mask:0xf bank_mask:0xf
	v_mov_b32_dpp v173, v81 row_newbcast:0 row_mask:0xf bank_mask:0xf
	v_mov_b32_dpp v174, v82 row_newbcast:0 row_mask:0xf bank_mask:0xf
	v_mov_b32_dpp v175, v83 row_newbcast:0 row_mask:0xf bank_mask:0xf
	v_exp_f32_e32 v88, v236
	v_exp_f32_e32 v80, v240
	v_add_f32_e32 v88, 1.0, v88
	v_rcp_f32_e32 v88, v88
	v_add_f32_e32 v80, 1.0, v80
	v_rcp_f32_e32 v80, v80
	v_exp_f32_e32 v81, v241
	v_mul_f32_e32 v84, v228, v88
	v_exp_f32_e32 v84, v84
	v_mul_f32_e32 v80, v116, v80
	v_add_f32_e32 v81, 1.0, v81
	v_rcp_f32_e32 v81, v81
	v_fma_f32 v88, -v84, v84, 1.0
	v_sqrt_f32_e32 v88, v88
	v_mul_f32_e32 v81, v117, v81
	v_exp_f32_e32 v82, v242
	v_mul_f32_e32 v80, v80, v88
	v_exp_f32_e32 v88, v237
	v_add_f32_e32 v82, 1.0, v82
	v_rcp_f32_e32 v82, v82
	v_add_f32_e32 v88, 1.0, v88
	v_rcp_f32_e32 v88, v88
	v_mul_f32_e32 v82, v114, v82
	v_exp_f32_e32 v83, v243
	v_mul_f32_e32 v85, v229, v88
	v_exp_f32_e32 v88, v85
	v_add_f32_e32 v83, 1.0, v83
	v_rcp_f32_e32 v83, v83
	v_fma_f32 v85, -v88, v88, 1.0
	v_sqrt_f32_e32 v85, v85
	v_mul_f32_e32 v83, v115, v83
	v_mul_f32_e32 v81, v81, v85
	v_exp_f32_e32 v85, v238
	s_nop 0
	v_add_f32_e32 v85, 1.0, v85
; __device__ __forceinline__ unsigned pk2(float lo, float hi) { return pg8::cvt_pk_bf16(lo, hi); }
; __device__ __forceinline__ float bflo(unsigned w) { return __uint_as_float(w << 16); }
; __device__ __forceinline__ float bfhi(unsigned w) { return __uint_as_float(w & 0xffff0000u); }
; template <int PASS> __device__ __forceinline__ void phase_lru(LAS unsigned char* lds, const bf16_t* Z, const bf16_t* WL, float* LSUM, const float* LCAR, bf16_t* RNN,
;                                                               int S, int tid, int lane, int wave, int G) {
;     ...
;                     for (int j = 0; j < 4; ++j) {
;                         const float rg = __builtin_amdgcn_rcpf(1.0f + __builtin_amdgcn_exp2f(fmaf(gr[j], -LOG2E, kba[j])));
;                         const float ig = __builtin_amdgcn_rcpf(1.0f + __builtin_amdgcn_exp2f(fmaf(gi[j], -LOG2E, kbx[j])));
;                         const float a_ = __builtin_amdgcn_exp2f(rg * ksp[j]);
;                         av[j] = a_; hv[j] = __builtin_amdgcn_sqrtf(fmaf(-a_, a_, 1.0f)) * (ig * xc[t][j]);
;                     }
;                     lru_scan4_bwd(av, hv);
; #pragma unroll
;                     for (int j = 0; j < 4; ++j) {
;                         const float hfull = fmaf(av[j], Hc[j], hv[j]);
;                         Hc[j] = __shfl(hfull, lane & 48);
;                         if (PASS == 0) Ac[j] *= __shfl(av[j], lane & 48);
;                         if (PASS == 1) { const unsigned rw = j < 2 ? ryr[t].x : ryr[t].y; const float y = (j & 1) ? bfhi(rw) : bflo(rw);
;                             const float ge = y * __builtin_amdgcn_rcpf(1.0f + __builtin_amdgcn_exp2f((-2.3022082f * y) * fmaf(0.044715f * y, y, 1.0f)));
;                             ov[j] = (hf[t][j] + hfull) * ge; }
;                     }
;                     if (PASS == 1) { u32x2 w; w.x = pk2(ov[0], ov[1]); w.y = pk2(ov[2], ov[3]); *(u32x2*)(RNN + (size_t)(t0 + 16 * t + c) * LW + ch0) = w; }
;                     __builtin_amdgcn_sched_barrier(0);
;                 }
;                 if (PASS == 0 && c == 0) {
; #pragma unroll
;                     for (int j = 0; j < 4; ++j) { float* sp = LSUM + ((size_t)(seg * 2 + 1) * LW + ch0 + j) * 2; sp[0] = Ac[j]; sp[1] = Hc[j]; }
;                 }
	v_rcp_f32_e32 v85, v85
	s_nop 0
	v_mul_f32_e32 v85, v230, v85
	v_exp_f32_e32 v89, v85
	s_nop 0
	v_fma_f32 v85, -v89, v89, 1.0
	v_sqrt_f32_e32 v85, v85
	s_nop 0
	v_mul_f32_e32 v82, v82, v85
	v_exp_f32_e32 v85, v239
	s_nop 0
	v_add_f32_e32 v85, 1.0, v85
	v_rcp_f32_e32 v85, v85
	s_nop 0
	v_mul_f32_e32 v85, v231, v85
	v_exp_f32_e32 v90, v85
	s_nop 0
	v_fma_f32 v85, -v90, v90, 1.0
	v_sqrt_f32_e32 v85, v85
	s_nop 0
	v_mul_f32_e32 v91, v83, v85
	s_nop 1
	v_fmac_f32_dpp v80, v80, v84 row_shl:1 row_mask:0xf bank_mask:0xf
	v_fmac_f32_dpp v81, v81, v88 row_shl:1 row_mask:0xf bank_mask:0xf
	v_fmac_f32_dpp v82, v82, v89 row_shl:1 row_mask:0xf bank_mask:0xf
	v_fmac_f32_dpp v91, v91, v90 row_shl:1 row_mask:0xf bank_mask:0xf
	v_mul_f32_dpp v84, v84, v84 row_shl:1 row_mask:0xf bank_mask:0xf
	v_mul_f32_dpp v88, v88, v88 row_shl:1 row_mask:0xf bank_mask:0xf
	v_mul_f32_dpp v89, v89, v89 row_shl:1 row_mask:0xf bank_mask:0xf
	v_mul_f32_dpp v90, v90, v90 row_shl:1 row_mask:0xf bank_mask:0xf
	v_fmac_f32_dpp v80, v80, v84 row_shl:2 row_mask:0xf bank_mask:0xf
	v_fmac_f32_dpp v81, v81, v88 row_shl:2 row_mask:0xf bank_mask:0xf
	v_fmac_f32_dpp v82, v82, v89 row_shl:2 row_mask:0xf bank_mask:0xf
	v_fmac_f32_dpp v91, v91, v90 row_shl:2 row_mask:0xf bank_mask:0xf
	v_mul_f32_dpp v84, v84, v84 row_shl:2 row_mask:0xf bank_mask:0xf
	v_mul_f32_dpp v88, v88, v88 row_shl:2 row_mask:0xf bank_mask:0xf
	v_mul_f32_dpp v89, v89, v89 row_shl:2 row_mask:0xf bank_mask:0xf
	v_mul_f32_dpp v90, v90, v90 row_shl:2 row_mask:0xf bank_mask:0xf
	v_fmac_f32_dpp v80, v80, v84 row_shl:4 row_mask:0xf bank_mask:0xf
	v_fmac_f32_dpp v81, v81, v88 row_shl:4 row_mask:0xf bank_mask:0xf
	v_fmac_f32_dpp v82, v82, v89 row_shl:4 row_mask:0xf bank_mask:0xf
	v_fmac_f32_dpp v91, v91, v90 row_shl:4 row_mask:0xf bank_mask:0xf
	v_mul_f32_dpp v84, v84, v84 row_shl:4 row_mask:0xf bank_mask:0xf
	v_mul_f32_dpp v88, v88, v88 row_shl:4 row_mask:0xf bank_mask:0xf
	v_mul_f32_dpp v89, v89, v89 row_shl:4 row_mask:0xf bank_mask:0xf
	v_mul_f32_dpp v90, v90, v90 row_shl:4 row_mask:0xf bank_mask:0xf
	v_fmac_f32_dpp v80, v80, v84 row_shl:8 row_mask:0xf bank_mask:0xf
	v_fmac_f32_dpp v81, v81, v88 row_shl:8 row_mask:0xf bank_mask:0xf
	v_fmac_f32_dpp v82, v82, v89 row_shl:8 row_mask:0xf bank_mask:0xf
	v_fmac_f32_dpp v91, v91, v90 row_shl:8 row_mask:0xf bank_mask:0xf
	v_mul_f32_dpp v84, v84, v84 row_shl:8 row_mask:0xf bank_mask:0xf
	v_mul_f32_dpp v88, v88, v88 row_shl:8 row_mask:0xf bank_mask:0xf
	v_mul_f32_dpp v89, v89, v89 row_shl:8 row_mask:0xf bank_mask:0xf
	v_mul_f32_dpp v90, v90, v90 row_shl:8 row_mask:0xf bank_mask:0xf
	s_nop 1
	v_mov_b32_dpp v86, v84 row_newbcast:0 row_mask:0xf bank_mask:0xf
	v_fmac_f32_e32 v80, v84, v129
	v_fmac_f32_e32 v81, v88, v173
	v_fmac_f32_e32 v82, v89, v174
	v_fmac_f32_e32 v91, v90, v175
	v_mov_b32_dpp v87, v80 row_newbcast:0 row_mask:0xf bank_mask:0xf
	v_mov_b32_dpp v85, v81 row_newbcast:0 row_mask:0xf bank_mask:0xf
	v_mov_b32_dpp v84, v88 row_newbcast:0 row_mask:0xf bank_mask:0xf
	v_mov_b32_dpp v83, v82 row_newbcast:0 row_mask:0xf bank_mask:0xf
	v_mov_b32_dpp v82, v89 row_newbcast:0 row_mask:0xf bank_mask:0xf
	v_mov_b32_dpp v81, v91 row_newbcast:0 row_mask:0xf bank_mask:0xf
	v_mov_b32_dpp v80, v90 row_newbcast:0 row_mask:0xf bank_mask:0xf
	s_and_saveexec_b64 s[18:19], s[40:41]
	s_cbranch_execz .LBB0_220
	v_mul_f32_e32 v88, v128, v125
	v_mul_f32_e32 v88, v88, v121
	s_waitcnt lgkmcnt(0)
	v_mul_f32_e32 v80, v88, v80
	v_mul_f32_e32 v88, v127, v124
	v_mul_f32_e32 v88, v88, v120
	v_mul_f32_e32 v82, v88, v82
	v_mul_f32_e32 v88, v126, v123
	v_mul_f32_e32 v1, v1, v122
	v_mul_f32_e32 v88, v88, v119
	v_mul_f32_e32 v1, v1, v118
	v_add_co_u32_e32 v90, vcc, 0x8303000, v144
	v_mul_f32_e32 v84, v88, v84
	v_mul_f32_e32 v86, v1, v86
	v_lshl_add_u64 v[88:89], v[146:147], 0, s[50:51]
	v_addc_co_u32_e32 v91, vcc, 0, v145, vcc
	global_store_dwordx2 v[90:91], v[86:87], off
	v_or_b32_e32 v86, 8, v88
	v_mov_b32_e32 v87, v89
	v_lshl_add_u64 v[86:87], s[10:11], 0, v[86:87]
	global_store_dwordx2 v[86:87], v[84:85], off
	v_or_b32_e32 v84, 16, v88
	v_mov_b32_e32 v85, v89
	v_lshl_add_u64 v[84:85], s[10:11], 0, v[84:85]
	v_or_b32_e32 v88, 24, v88
	global_store_dwordx2 v[84:85], v[82:83], off
	v_lshl_add_u64 v[82:83], s[10:11], 0, v[88:89]
	global_store_dwordx2 v[82:83], v[80:81], off
	s_branch .LBB0_220
